# ResNorm epilogue row sums: ds_bpermute xor16/xor32 replaced by v_permlane16/32_swap (no LDS round trips)
# speedup vs baseline: 1.0066x; 1.0066x over previous
;     __device__ __forceinline__ void operator()(const f32x4 (&acc)[2][2][4][2], const Unit& u, int wr, int wc, int fr, int fq) const {
;     ...
;         f32x4 g[2][2];
; #pragma unroll
;         for (int bj = 0; bj < 2; ++bj) { g[bj][0] = *(const f32x4*)(ga + colb + bj * 128); g[bj][1] = *(const f32x4*)(ga + colb + bj * 128 + 4); }
;         u32x4 pre[4][2];
; #pragma unroll
;         for (int m = 0; m < 4; ++m)
; #pragma unroll
;             for (int bj = 0; bj < 2; ++bj) pre[m][bj] = *(const u32x4*)(HB + (grow0 + rloc0 + m * 16) * DM + colb + bj * 128);
; #pragma unroll
;         for (int ai = 0; ai < 2; ++ai)
; #pragma unroll
;             for (int m = 0; m < 4; ++m) { float q = 0.f;
; #pragma unroll
;                 for (int bj = 0; bj < 2; ++bj)
; #pragma unroll
;                     for (int n = 0; n < 2; ++n) { const f32x4 x = acc[ai][bj][m][n]; q += (x[0] * x[0] + x[1] * x[1]) + (x[2] * x[2] + x[3] * x[3]); }
;                 q += __shfl_xor(q, 16); q += __shfl_xor(q, 32);
;                 if (fq == 0) P[(rloc0 + ai * 128 + m * 16) * 4 + wc] = q; }
.LBB0_458:
	s_ashr_i32 s63, s62, 31
	v_lshl_or_b32 v218, s38, 8, v223
	s_lshl_b64 s[36:37], s[62:63], 8
	v_ashrrev_i32_e32 v219, 31, v218
	v_lshl_add_u64 v[146:147], s[36:37], 0, v[192:193]
	v_lshl_add_u64 v[148:149], v[218:219], 1, s[58:59]
	v_lshlrev_b64 v[174:175], 11, v[146:147]
	v_lshl_add_u64 v[146:147], v[148:149], 0, v[174:175]
	v_add_co_u32_e32 v148, vcc, s72, v146
	v_lshl_add_u64 v[94:95], v[218:219], 2, s[16:17]
	s_nop 0
	v_addc_co_u32_e32 v149, vcc, 0, v147, vcc
	s_mov_b32 s9, 0x10000
	global_load_dwordx4 v[98:101], v[94:95], off offset:16
	global_load_dwordx4 v[102:105], v[94:95], off
	global_load_dwordx4 v[90:93], v[94:95], off offset:528
	s_nop 0
	global_load_dwordx4 v[94:97], v[94:95], off offset:512
	s_nop 0
	global_load_dwordx4 v[178:181], v[146:147], off
	global_load_dwordx4 v[170:173], v[146:147], off offset:256
	global_load_dwordx4 v[166:169], v[148:149], off
	global_load_dwordx4 v[162:165], v[148:149], off offset:256
	v_add_co_u32_e32 v148, vcc, s9, v146
	s_mov_b32 s9, 0x18000
	s_nop 0
	v_addc_co_u32_e32 v149, vcc, 0, v147, vcc
	v_add_co_u32_e32 v146, vcc, s9, v146
	global_load_dwordx4 v[158:161], v[148:149], off
	global_load_dwordx4 v[154:157], v[148:149], off offset:256
	v_addc_co_u32_e32 v147, vcc, 0, v147, vcc
	global_load_dwordx4 v[150:153], v[146:147], off
	s_nop 0
	global_load_dwordx4 v[146:149], v[146:147], off offset:256
	v_and_b32_e32 v177, 64, v237
	v_xor_b32_e32 v176, 16, v237
	v_add_u32_e32 v177, 64, v177
	v_cmp_lt_i32_e32 vcc, v176, v177
	v_mul_f32_e32 v182, v145, v145
	v_fmac_f32_e32 v182, v144, v144
	v_cndmask_b32_e32 v176, v237, v176, vcc
	v_lshlrev_b32_e32 v239, 2, v176
	v_mul_f32_e32 v176, v143, v143
	v_fmac_f32_e32 v176, v142, v142
	v_add_f32_e32 v176, v176, v182
	v_mul_f32_e32 v182, v139, v139
	v_mul_f32_e32 v183, v141, v141
	v_fmac_f32_e32 v182, v138, v138
	v_fmac_f32_e32 v183, v140, v140
	v_add_f32_e32 v182, v182, v183
	v_add_f32_e32 v176, v176, v182
	v_mul_f32_e32 v182, v135, v135
	v_mul_f32_e32 v183, v137, v137
	v_fmac_f32_e32 v182, v134, v134
	v_fmac_f32_e32 v183, v136, v136
	v_add_f32_e32 v182, v182, v183
	v_add_f32_e32 v176, v176, v182
	v_mul_f32_e32 v182, v131, v131
	v_mul_f32_e32 v183, v133, v133
	v_fmac_f32_e32 v182, v130, v130
	v_fmac_f32_e32 v183, v132, v132
	v_add_f32_e32 v182, v182, v183
	v_add_f32_e32 v176, v176, v182
	v_mov_b32_e32 v182, v176
	s_nop 1
	v_permlane16_swap_b32_e32 v182, v176
	v_xor_b32_e32 v183, 32, v237
	v_cmp_lt_i32_e32 vcc, v183, v177
	s_waitcnt lgkmcnt(0)
	v_add_f32_e32 v176, v176, v182
	v_cndmask_b32_e32 v177, v237, v183, vcc
	v_lshlrev_b32_e32 v240, 2, v177
	v_mov_b32_e32 v177, v176
	s_nop 1
	v_permlane32_swap_b32_e32 v177, v176
	s_and_saveexec_b64 s[54:55], s[44:45]
	s_cbranch_execz .LBB0_460
	s_waitcnt lgkmcnt(0)
	v_add_f32_e32 v176, v176, v177
	ds_write_b32 v224, v176
.LBB0_460:
	s_or_b64 exec, exec, s[54:55]
	v_mul_f32_e32 v176, v127, v127
	s_waitcnt lgkmcnt(0)
	v_mul_f32_e32 v177, v129, v129
	v_fmac_f32_e32 v176, v126, v126
	v_fmac_f32_e32 v177, v128, v128
	v_add_f32_e32 v176, v176, v177
	v_mul_f32_e32 v177, v123, v123
	v_mul_f32_e32 v182, v125, v125
	v_fmac_f32_e32 v177, v122, v122
	v_fmac_f32_e32 v182, v124, v124
	v_add_f32_e32 v177, v177, v182
	v_add_f32_e32 v176, v176, v177
	v_mul_f32_e32 v177, v119, v119
	v_mul_f32_e32 v182, v121, v121
	v_fmac_f32_e32 v177, v118, v118
	v_fmac_f32_e32 v182, v120, v120
	v_add_f32_e32 v177, v177, v182
	v_add_f32_e32 v176, v176, v177
	v_mul_f32_e32 v177, v115, v115
	v_mul_f32_e32 v182, v117, v117
	v_fmac_f32_e32 v177, v114, v114
	v_fmac_f32_e32 v182, v116, v116
	v_add_f32_e32 v177, v177, v182
	v_add_f32_e32 v176, v176, v177
	v_mov_b32_e32 v177, v176
	s_nop 1
	v_permlane16_swap_b32_e32 v177, v176
	s_waitcnt lgkmcnt(0)
	v_add_f32_e32 v176, v176, v177
	v_mov_b32_e32 v177, v176
	s_nop 1
	v_permlane32_swap_b32_e32 v177, v176
	s_and_saveexec_b64 s[54:55], s[44:45]
	s_cbranch_execz .LBB0_462
	s_waitcnt lgkmcnt(0)
	v_add_f32_e32 v176, v176, v177
	ds_write_b32 v224, v176 offset:256
.LBB0_462:
	s_or_b64 exec, exec, s[54:55]
	v_mul_f32_e32 v176, v111, v111
	s_waitcnt lgkmcnt(0)
	v_mul_f32_e32 v177, v113, v113
	v_fmac_f32_e32 v176, v110, v110
	v_fmac_f32_e32 v177, v112, v112
	v_add_f32_e32 v176, v176, v177
	v_mul_f32_e32 v177, v107, v107
	v_mul_f32_e32 v182, v109, v109
	v_fmac_f32_e32 v177, v106, v106
	v_fmac_f32_e32 v182, v108, v108
	v_add_f32_e32 v177, v177, v182
	v_add_f32_e32 v176, v176, v177
	v_mul_f32_e32 v177, v87, v87
	v_mul_f32_e32 v182, v89, v89
	v_fmac_f32_e32 v177, v86, v86
	v_fmac_f32_e32 v182, v88, v88
	v_add_f32_e32 v177, v177, v182
	v_add_f32_e32 v176, v176, v177
	v_mul_f32_e32 v177, v83, v83
	v_mul_f32_e32 v182, v85, v85
	v_fmac_f32_e32 v177, v82, v82
	v_fmac_f32_e32 v182, v84, v84
	v_add_f32_e32 v177, v177, v182
	v_add_f32_e32 v176, v176, v177
	v_mov_b32_e32 v177, v176
	s_nop 1
	v_permlane16_swap_b32_e32 v177, v176
	s_waitcnt lgkmcnt(0)
	v_add_f32_e32 v176, v176, v177
	v_mov_b32_e32 v177, v176
	s_nop 1
	v_permlane32_swap_b32_e32 v177, v176
	s_and_saveexec_b64 s[54:55], s[44:45]
	s_cbranch_execz .LBB0_464
	s_waitcnt lgkmcnt(0)
	v_add_f32_e32 v176, v176, v177
	ds_write_b32 v224, v176 offset:512
;     __device__ __forceinline__ void operator()(const f32x4 (&acc)[2][2][4][2], const Unit& u, int wr, int wc, int fr, int fq) const {
;     ...
;         for (int ai = 0; ai < 2; ++ai)
; #pragma unroll
;             for (int m = 0; m < 4; ++m) { float q = 0.f;
; #pragma unroll
;                 for (int bj = 0; bj < 2; ++bj)
; #pragma unroll
;                     for (int n = 0; n < 2; ++n) { const f32x4 x = acc[ai][bj][m][n]; q += (x[0] * x[0] + x[1] * x[1]) + (x[2] * x[2] + x[3] * x[3]); }
;                 q += __shfl_xor(q, 16); q += __shfl_xor(q, 32);
;                 if (fq == 0) P[(rloc0 + ai * 128 + m * 16) * 4 + wc] = q; }
.LBB0_464:
	s_or_b64 exec, exec, s[54:55]
	v_mul_f32_e32 v176, v79, v79
	s_waitcnt lgkmcnt(0)
	v_mul_f32_e32 v177, v81, v81
	v_fmac_f32_e32 v176, v78, v78
	v_fmac_f32_e32 v177, v80, v80
	v_add_f32_e32 v176, v176, v177
	v_mul_f32_e32 v177, v75, v75
	v_mul_f32_e32 v182, v77, v77
	v_fmac_f32_e32 v177, v74, v74
	v_fmac_f32_e32 v182, v76, v76
	v_add_f32_e32 v177, v177, v182
	v_add_f32_e32 v176, v176, v177
	v_mul_f32_e32 v177, v71, v71
	v_mul_f32_e32 v182, v73, v73
	v_fmac_f32_e32 v177, v70, v70
	v_fmac_f32_e32 v182, v72, v72
	v_add_f32_e32 v177, v177, v182
	v_add_f32_e32 v176, v176, v177
	v_mul_f32_e32 v177, v67, v67
	v_mul_f32_e32 v182, v69, v69
	v_fmac_f32_e32 v177, v66, v66
	v_fmac_f32_e32 v182, v68, v68
	v_add_f32_e32 v177, v177, v182
	v_add_f32_e32 v176, v176, v177
	v_mov_b32_e32 v177, v176
	s_nop 1
	v_permlane16_swap_b32_e32 v177, v176
	s_waitcnt lgkmcnt(0)
	v_add_f32_e32 v176, v176, v177
	v_mov_b32_e32 v177, v176
	s_nop 1
	v_permlane32_swap_b32_e32 v177, v176
	s_and_saveexec_b64 s[54:55], s[44:45]
	s_cbranch_execz .LBB0_466
	s_waitcnt lgkmcnt(0)
	v_add_f32_e32 v176, v176, v177
	ds_write_b32 v224, v176 offset:768
.LBB0_466:
	s_or_b64 exec, exec, s[54:55]
	v_mul_f32_e32 v176, v63, v63
	s_waitcnt lgkmcnt(0)
	v_mul_f32_e32 v177, v65, v65
	v_fmac_f32_e32 v176, v62, v62
	v_fmac_f32_e32 v177, v64, v64
	v_add_f32_e32 v176, v176, v177
	v_mul_f32_e32 v177, v59, v59
	v_mul_f32_e32 v182, v61, v61
	v_fmac_f32_e32 v177, v58, v58
	v_fmac_f32_e32 v182, v60, v60
	v_add_f32_e32 v177, v177, v182
	v_add_f32_e32 v176, v176, v177
	v_mul_f32_e32 v177, v55, v55
	v_mul_f32_e32 v182, v57, v57
	v_fmac_f32_e32 v177, v54, v54
	v_fmac_f32_e32 v182, v56, v56
	v_add_f32_e32 v177, v177, v182
	v_add_f32_e32 v176, v176, v177
	v_mul_f32_e32 v177, v51, v51
	v_mul_f32_e32 v182, v53, v53
	v_fmac_f32_e32 v177, v50, v50
	v_fmac_f32_e32 v182, v52, v52
	v_add_f32_e32 v177, v177, v182
	v_add_f32_e32 v176, v176, v177
	v_mov_b32_e32 v177, v176
	s_nop 1
	v_permlane16_swap_b32_e32 v177, v176
	s_waitcnt lgkmcnt(0)
	v_add_f32_e32 v176, v176, v177
	v_mov_b32_e32 v177, v176
	s_nop 1
	v_permlane32_swap_b32_e32 v177, v176
	s_and_saveexec_b64 s[54:55], s[44:45]
	s_cbranch_execz .LBB0_468
	s_waitcnt lgkmcnt(0)
	v_add_f32_e32 v176, v176, v177
	ds_write_b32 v224, v176 offset:2048
.LBB0_468:
	s_or_b64 exec, exec, s[54:55]
	v_mul_f32_e32 v176, v47, v47
	s_waitcnt lgkmcnt(0)
	v_mul_f32_e32 v177, v49, v49
	v_fmac_f32_e32 v176, v46, v46
	v_fmac_f32_e32 v177, v48, v48
	v_add_f32_e32 v176, v176, v177
	v_mul_f32_e32 v177, v43, v43
	v_mul_f32_e32 v182, v45, v45
	v_fmac_f32_e32 v177, v42, v42
	v_fmac_f32_e32 v182, v44, v44
	v_add_f32_e32 v177, v177, v182
	v_add_f32_e32 v176, v176, v177
	v_mul_f32_e32 v177, v39, v39
	v_mul_f32_e32 v182, v41, v41
	v_fmac_f32_e32 v177, v38, v38
	v_fmac_f32_e32 v182, v40, v40
	v_add_f32_e32 v177, v177, v182
	v_add_f32_e32 v176, v176, v177
	v_mul_f32_e32 v177, v35, v35
	v_mul_f32_e32 v182, v37, v37
	v_fmac_f32_e32 v177, v34, v34
	v_fmac_f32_e32 v182, v36, v36
	v_add_f32_e32 v177, v177, v182
	v_add_f32_e32 v176, v176, v177
	v_mov_b32_e32 v177, v176
	s_nop 1
	v_permlane16_swap_b32_e32 v177, v176
	s_waitcnt lgkmcnt(0)
	v_add_f32_e32 v176, v176, v177
	v_mov_b32_e32 v177, v176
	s_nop 1
	v_permlane32_swap_b32_e32 v177, v176
	s_and_saveexec_b64 s[54:55], s[44:45]
	s_cbranch_execz .LBB0_470
	s_waitcnt lgkmcnt(0)
	v_add_f32_e32 v176, v176, v177
	ds_write_b32 v224, v176 offset:2304
.LBB0_470:
	s_or_b64 exec, exec, s[54:55]
	v_mul_f32_e32 v176, v31, v31
	s_waitcnt lgkmcnt(0)
	v_mul_f32_e32 v177, v33, v33
	v_fmac_f32_e32 v176, v30, v30
	v_fmac_f32_e32 v177, v32, v32
	v_add_f32_e32 v176, v176, v177
	v_mul_f32_e32 v177, v27, v27
	v_mul_f32_e32 v182, v29, v29
	v_fmac_f32_e32 v177, v26, v26
	v_fmac_f32_e32 v182, v28, v28
	v_add_f32_e32 v177, v177, v182
	v_add_f32_e32 v176, v176, v177
	v_mul_f32_e32 v177, v23, v23
	v_mul_f32_e32 v182, v25, v25
	v_fmac_f32_e32 v177, v22, v22
	v_fmac_f32_e32 v182, v24, v24
	v_add_f32_e32 v177, v177, v182
	v_add_f32_e32 v176, v176, v177
	v_mul_f32_e32 v177, v19, v19
	v_mul_f32_e32 v182, v21, v21
	v_fmac_f32_e32 v177, v18, v18
	v_fmac_f32_e32 v182, v20, v20
	v_add_f32_e32 v177, v177, v182
	v_add_f32_e32 v176, v176, v177
	v_mov_b32_e32 v177, v176
	s_nop 1
	v_permlane16_swap_b32_e32 v177, v176
	s_waitcnt lgkmcnt(0)
	v_add_f32_e32 v176, v176, v177
	v_mov_b32_e32 v177, v176
	s_nop 1
	v_permlane32_swap_b32_e32 v177, v176
	s_and_saveexec_b64 s[54:55], s[44:45]
	s_cbranch_execz .LBB0_472
	s_waitcnt lgkmcnt(0)
	v_add_f32_e32 v176, v176, v177
	ds_write_b32 v224, v176 offset:2560
.LBB0_472:
	s_or_b64 exec, exec, s[54:55]
	v_mul_f32_e32 v176, v15, v15
	s_waitcnt lgkmcnt(0)
	v_mul_f32_e32 v177, v17, v17
	v_fmac_f32_e32 v176, v14, v14
	v_fmac_f32_e32 v177, v16, v16
	v_add_f32_e32 v176, v176, v177
	v_mul_f32_e32 v177, v11, v11
	v_mul_f32_e32 v182, v13, v13
	v_fmac_f32_e32 v177, v10, v10
	v_fmac_f32_e32 v182, v12, v12
	v_add_f32_e32 v177, v177, v182
	v_add_f32_e32 v176, v176, v177
	v_mul_f32_e32 v177, v7, v7
	v_mul_f32_e32 v182, v9, v9
	v_fmac_f32_e32 v177, v6, v6
	v_fmac_f32_e32 v182, v8, v8
	v_add_f32_e32 v177, v177, v182
	v_add_f32_e32 v176, v176, v177
	v_mul_f32_e32 v177, v3, v3
	v_mul_f32_e32 v182, v5, v5
	v_fmac_f32_e32 v177, v2, v2
	v_fmac_f32_e32 v182, v4, v4
	v_add_f32_e32 v177, v177, v182
	v_add_f32_e32 v176, v176, v177
	v_mov_b32_e32 v177, v176
	s_nop 1
	v_permlane16_swap_b32_e32 v177, v176
	s_waitcnt lgkmcnt(0)
	v_add_f32_e32 v176, v176, v177
	v_mov_b32_e32 v177, v176
	s_nop 1
	v_permlane32_swap_b32_e32 v177, v176
	s_and_saveexec_b64 s[54:55], s[44:45]
	s_cbranch_execz .LBB0_474
	s_waitcnt lgkmcnt(0)
	v_add_f32_e32 v176, v176, v177
	ds_write_b32 v224, v176 offset:2816

; __device__ __forceinline__ unsigned cvt_pk_bf16(float lo, float hi) { unsigned r; asm volatile("v_cvt_pk_bf16_f32 %0, %1, %2" : "=v"(r) : "v"(lo), "v"(hi)); return r; }
; __device__ __forceinline__ void unpack8(const u32x4 w, float (&v)[8]) { v[0] = bf_lo(w.x); v[1] = bf_hi(w.x); v[2] = bf_lo(w.y); v[3] = bf_hi(w.y); v[4] = bf_lo(w.z); v[5] = bf_hi(w.z); v[6] = bf_lo(w.w); v[7] = bf_hi(w.w); }
;     __device__ __forceinline__ void operator()(const f32x4 (&acc)[2][2][4][2], const Unit& u, int wr, int wc, int fr, int fq) const {
;     ...
;         for (int ai = 0; ai < 2; ++ai)
; #pragma unroll
;             for (int m = 0; m < 4; ++m) { const int rloc = rloc0 + ai * 128 + m * 16; const float rs = S[rloc]; float q2 = 0.f;
;                 u32x4 cur[2]; cur[0] = pre[m][0]; cur[1] = pre[m][1];
;                 if (ai == 0) {
; #pragma unroll
;                     for (int bj = 0; bj < 2; ++bj) pre[m][bj] = *(const u32x4*)(HB + (grow0 + rloc + 128) * DM + colb + bj * 128); }
; #pragma unroll
;                 for (int bj = 0; bj < 2; ++bj) { float h[8]; unpack8(cur[bj], h);
; #pragma unroll
;                     for (int e = 0; e < 4; ++e) { h[e] += acc[ai][bj][m][0][e] * g[bj][0][e] * rs; h[4 + e] += acc[ai][bj][m][1][e] * g[bj][1][e] * rs; }
;                     if (OUT) { float* op = OUT + (grow0 + rloc) * DM + colb + bj * 128; *(f32x4*)op = (f32x4){h[0], h[1], h[2], h[3]}; *(f32x4*)(op + 4) = (f32x4){h[4], h[5], h[6], h[7]}; }
;                     else { u32x4 w; w.x = cvt_pk_bf16(h[0], h[1]); w.y = cvt_pk_bf16(h[2], h[3]); w.z = cvt_pk_bf16(h[4], h[5]); w.w = cvt_pk_bf16(h[6], h[7]);
;                         *(u32x4*)(HB + (grow0 + rloc) * DM + colb + bj * 128) = w; float qv[8]; unpack8(w, qv);
; #pragma unroll
;                         for (int e = 0; e < 8; ++e) q2 += qv[e] * qv[e]; } }
;                 q2 += __shfl_xor(q2, 16); q2 += __shfl_xor(q2, 32);
;                 if (fq == 0) P[rloc * 4 + wc] = q2; }
.LBB0_489:
	s_or_b64 exec, exec, s[62:63]
	v_lshl_add_u64 v[174:175], s[58:59], 0, v[174:175]
	v_lshl_add_u64 v[204:205], v[218:219], 1, v[174:175]
	s_mov_b32 s9, 0x40000
	v_add_co_u32_e32 v176, vcc, s9, v204
	s_waitcnt vmcnt(0) lgkmcnt(0)
	s_barrier
	v_lshl_add_u64 v[174:175], v[204:205], 0, s[24:25]
	s_waitcnt lgkmcnt(0)
	v_addc_co_u32_e32 v177, vcc, 0, v205, vcc
	ds_read_b32 v221, v225
	global_load_dwordx4 v[182:185], v[176:177], off
	s_nop 0
	global_load_dwordx4 v[174:177], v[174:175], off offset:256
	s_waitcnt vmcnt(2)
	v_lshlrev_b32_e32 v241, 16, v180
	v_mul_f32_e32 v138, v138, v98
	v_lshlrev_b32_e32 v234, 16, v178
	v_and_b32_e32 v178, 0xffff0000, v178
	s_waitcnt lgkmcnt(0)
	v_fmac_f32_e32 v241, v138, v221
	v_mul_f32_e32 v138, v143, v103
	v_and_b32_e32 v180, 0xffff0000, v180
	v_fmac_f32_e32 v178, v138, v221
	v_mul_f32_e32 v138, v139, v99
	v_lshlrev_b32_e32 v235, 16, v179
	v_fmac_f32_e32 v180, v138, v221
	v_mul_f32_e32 v138, v144, v104
	v_lshlrev_b32_e32 v242, 16, v181
	v_fmac_f32_e32 v235, v138, v221
	v_mul_f32_e32 v138, v140, v100
	v_and_b32_e32 v179, 0xffff0000, v179
	v_fmac_f32_e32 v242, v138, v221
	v_mul_f32_e32 v138, v145, v105
	v_and_b32_e32 v181, 0xffff0000, v181
	v_mul_f32_e32 v142, v142, v102
	v_fmac_f32_e32 v179, v138, v221
	v_mul_f32_e32 v138, v141, v101
	v_fmac_f32_e32 v234, v142, v221
	v_fmac_f32_e32 v181, v138, v221
	v_cvt_pk_bf16_f32 v138, v234, v178
	v_cvt_pk_bf16_f32 v139, v235, v179
	v_cvt_pk_bf16_f32 v140, v241, v180
	v_cvt_pk_bf16_f32 v141, v242, v181
	global_store_dwordx4 v[204:205], v[138:141], off
	v_lshlrev_b32_e32 v142, 16, v138
	v_lshlrev_b32_e32 v143, 16, v139
	v_and_b32_e32 v138, 0xffff0000, v138
	v_mul_f32_e32 v138, v138, v138
	v_fmac_f32_e32 v138, v142, v142
	v_and_b32_e32 v139, 0xffff0000, v139
	v_fmac_f32_e32 v138, v143, v143
	v_lshlrev_b32_e32 v144, 16, v140
	v_fmac_f32_e32 v138, v139, v139
	v_and_b32_e32 v140, 0xffff0000, v140
	v_fmac_f32_e32 v138, v144, v144
	v_lshlrev_b32_e32 v143, 16, v172
	v_mul_f32_e32 v130, v130, v90
	v_lshlrev_b32_e32 v145, 16, v141
	v_fmac_f32_e32 v138, v140, v140
	v_and_b32_e32 v140, 0xffff0000, v170
	v_fmac_f32_e32 v143, v130, v221
	v_mul_f32_e32 v130, v135, v95
	v_and_b32_e32 v141, 0xffff0000, v141
	v_fmac_f32_e32 v138, v145, v145
	v_and_b32_e32 v144, 0xffff0000, v172
	v_fmac_f32_e32 v140, v130, v221
	v_mul_f32_e32 v130, v131, v91
	v_fmac_f32_e32 v138, v141, v141
	v_lshlrev_b32_e32 v141, 16, v171
	v_fmac_f32_e32 v144, v130, v221
	v_mul_f32_e32 v130, v136, v96
	v_lshlrev_b32_e32 v145, 16, v173
	v_fmac_f32_e32 v141, v130, v221
	v_mul_f32_e32 v130, v132, v92
	v_and_b32_e32 v142, 0xffff0000, v171
	v_fmac_f32_e32 v145, v130, v221
	v_mul_f32_e32 v130, v137, v97
	v_lshlrev_b32_e32 v139, 16, v170
	v_and_b32_e32 v170, 0xffff0000, v173
	v_mul_f32_e32 v134, v134, v94
	v_fmac_f32_e32 v142, v130, v221
	v_mul_f32_e32 v130, v133, v93
	v_fmac_f32_e32 v139, v134, v221
	v_fmac_f32_e32 v170, v130, v221
	v_cvt_pk_bf16_f32 v132, v139, v140
	v_cvt_pk_bf16_f32 v133, v141, v142
	v_cvt_pk_bf16_f32 v134, v143, v144
	v_cvt_pk_bf16_f32 v135, v145, v170
	global_store_dwordx4 v[204:205], v[132:135], off offset:256
	v_lshlrev_b32_e32 v130, 16, v132
	v_and_b32_e32 v131, 0xffff0000, v132
	v_fmac_f32_e32 v138, v130, v130
	v_lshlrev_b32_e32 v136, 16, v133
	v_fmac_f32_e32 v138, v131, v131
	v_and_b32_e32 v137, 0xffff0000, v133
	v_fmac_f32_e32 v138, v136, v136
	v_lshlrev_b32_e32 v139, 16, v134
	v_fmac_f32_e32 v138, v137, v137
	v_and_b32_e32 v140, 0xffff0000, v134
	v_fmac_f32_e32 v138, v139, v139
	v_lshlrev_b32_e32 v141, 16, v135
	v_fmac_f32_e32 v138, v140, v140
	v_and_b32_e32 v142, 0xffff0000, v135
	v_fmac_f32_e32 v138, v141, v141
	v_fmac_f32_e32 v138, v142, v142
	v_mov_b32_e32 v130, v138
	s_nop 1
	v_permlane16_swap_b32_e32 v130, v138
	s_waitcnt lgkmcnt(0)
	v_add_f32_e32 v130, v138, v130
	v_mov_b32_e32 v131, v130
	s_nop 1
	v_permlane32_swap_b32_e32 v131, v130
	s_and_saveexec_b64 s[54:55], s[44:45]
	s_cbranch_execz .LBB0_491
	s_waitcnt lgkmcnt(0)
	v_add_f32_e32 v130, v130, v131
	ds_write_b32 v224, v130
.LBB0_491:
	s_or_b64 exec, exec, s[54:55]
	v_lshl_add_u32 v130, v194, 2, s64
	ds_read_b32 v140, v130
	s_waitcnt lgkmcnt(1)
	v_lshl_add_u64 v[130:131], s[36:37], 0, v[194:195]
	v_lshlrev_b64 v[130:131], 11, v[130:131]
	v_lshl_add_u64 v[130:131], s[58:59], 0, v[130:131]
	v_lshl_add_u64 v[138:139], v[218:219], 1, v[130:131]
	v_add_co_u32_e32 v132, vcc, 0x40000, v138
	v_lshl_add_u64 v[130:131], v[138:139], 0, s[24:25]
	s_nop 0
	v_addc_co_u32_e32 v133, vcc, 0, v139, vcc
	global_load_dwordx4 v[134:137], v[132:133], off
	s_nop 0
	global_load_dwordx4 v[130:133], v[130:131], off offset:256
	v_lshlrev_b32_e32 v145, 16, v168
	v_mul_f32_e32 v122, v122, v98
	v_and_b32_e32 v142, 0xffff0000, v166
	s_waitcnt lgkmcnt(0)
; __device__ __forceinline__ unsigned cvt_pk_bf16(float lo, float hi) { unsigned r; asm volatile("v_cvt_pk_bf16_f32 %0, %1, %2" : "=v"(r) : "v"(lo), "v"(hi)); return r; }
; __device__ __forceinline__ void unpack8(const u32x4 w, float (&v)[8]) { v[0] = bf_lo(w.x); v[1] = bf_hi(w.x); v[2] = bf_lo(w.y); v[3] = bf_hi(w.y); v[4] = bf_lo(w.z); v[5] = bf_hi(w.z); v[6] = bf_lo(w.w); v[7] = bf_hi(w.w); }
;     __device__ __forceinline__ void operator()(const f32x4 (&acc)[2][2][4][2], const Unit& u, int wr, int wc, int fr, int fq) const {
;     ...
;         for (int ai = 0; ai < 2; ++ai)
; #pragma unroll
;             for (int m = 0; m < 4; ++m) { const int rloc = rloc0 + ai * 128 + m * 16; const float rs = S[rloc]; float q2 = 0.f;
;                 u32x4 cur[2]; cur[0] = pre[m][0]; cur[1] = pre[m][1];
;                 if (ai == 0) {
; #pragma unroll
;                     for (int bj = 0; bj < 2; ++bj) pre[m][bj] = *(const u32x4*)(HB + (grow0 + rloc + 128) * DM + colb + bj * 128); }
; #pragma unroll
;                 for (int bj = 0; bj < 2; ++bj) { float h[8]; unpack8(cur[bj], h);
; #pragma unroll
;                     for (int e = 0; e < 4; ++e) { h[e] += acc[ai][bj][m][0][e] * g[bj][0][e] * rs; h[4 + e] += acc[ai][bj][m][1][e] * g[bj][1][e] * rs; }
;                     if (OUT) { float* op = OUT + (grow0 + rloc) * DM + colb + bj * 128; *(f32x4*)op = (f32x4){h[0], h[1], h[2], h[3]}; *(f32x4*)(op + 4) = (f32x4){h[4], h[5], h[6], h[7]}; }
;                     else { u32x4 w; w.x = cvt_pk_bf16(h[0], h[1]); w.y = cvt_pk_bf16(h[2], h[3]); w.z = cvt_pk_bf16(h[4], h[5]); w.w = cvt_pk_bf16(h[6], h[7]);
;                         *(u32x4*)(HB + (grow0 + rloc) * DM + colb + bj * 128) = w; float qv[8]; unpack8(w, qv);
; #pragma unroll
;                         for (int e = 0; e < 8; ++e) q2 += qv[e] * qv[e]; } }
;                 q2 += __shfl_xor(q2, 16); q2 += __shfl_xor(q2, 32);
;                 if (fq == 0) P[rloc * 4 + wc] = q2; }
	v_fmac_f32_e32 v145, v122, v140
	v_mul_f32_e32 v122, v127, v103
	v_lshlrev_b32_e32 v141, 16, v166
	v_and_b32_e32 v166, 0xffff0000, v168
	v_fmac_f32_e32 v142, v122, v140
	v_mul_f32_e32 v122, v123, v99
	v_lshlrev_b32_e32 v143, 16, v167
	v_fmac_f32_e32 v166, v122, v140
	v_mul_f32_e32 v122, v128, v104
	v_and_b32_e32 v144, 0xffff0000, v167
	v_lshlrev_b32_e32 v167, 16, v169
	v_fmac_f32_e32 v143, v122, v140
	v_mul_f32_e32 v122, v124, v100
	v_fmac_f32_e32 v167, v122, v140
	v_mul_f32_e32 v122, v129, v105
	v_and_b32_e32 v168, 0xffff0000, v169
	v_mul_f32_e32 v126, v126, v102
	v_fmac_f32_e32 v144, v122, v140
	v_mul_f32_e32 v122, v125, v101
	v_fmac_f32_e32 v141, v126, v140
	v_fmac_f32_e32 v168, v122, v140
	v_cvt_pk_bf16_f32 v122, v141, v142
	v_cvt_pk_bf16_f32 v123, v143, v144
	v_cvt_pk_bf16_f32 v124, v145, v166
	v_cvt_pk_bf16_f32 v125, v167, v168
	global_store_dwordx4 v[138:139], v[122:125], off
	v_lshlrev_b32_e32 v126, 16, v122
	v_lshlrev_b32_e32 v127, 16, v123
	v_and_b32_e32 v122, 0xffff0000, v122
	v_mul_f32_e32 v122, v122, v122
	v_fmac_f32_e32 v122, v126, v126
	v_and_b32_e32 v123, 0xffff0000, v123
	v_fmac_f32_e32 v122, v127, v127
	v_lshlrev_b32_e32 v128, 16, v124
	v_fmac_f32_e32 v122, v123, v123
	v_and_b32_e32 v124, 0xffff0000, v124
	v_fmac_f32_e32 v122, v128, v128
	v_lshlrev_b32_e32 v127, 16, v164
	v_mul_f32_e32 v114, v114, v90
	v_lshlrev_b32_e32 v129, 16, v125
	v_fmac_f32_e32 v122, v124, v124
	v_and_b32_e32 v124, 0xffff0000, v162
	v_fmac_f32_e32 v127, v114, v140
	v_mul_f32_e32 v114, v119, v95
	v_and_b32_e32 v125, 0xffff0000, v125
	v_fmac_f32_e32 v122, v129, v129
	v_and_b32_e32 v128, 0xffff0000, v164
	v_fmac_f32_e32 v124, v114, v140
	v_mul_f32_e32 v114, v115, v91
	v_fmac_f32_e32 v122, v125, v125
	v_lshlrev_b32_e32 v125, 16, v163
	v_fmac_f32_e32 v128, v114, v140
	v_mul_f32_e32 v114, v120, v96
	v_lshlrev_b32_e32 v129, 16, v165
	v_fmac_f32_e32 v125, v114, v140
	v_mul_f32_e32 v114, v116, v92
	v_and_b32_e32 v126, 0xffff0000, v163
	v_fmac_f32_e32 v129, v114, v140
	v_mul_f32_e32 v114, v121, v97
	v_lshlrev_b32_e32 v123, 16, v162
	v_and_b32_e32 v141, 0xffff0000, v165
	v_mul_f32_e32 v118, v118, v94
	v_fmac_f32_e32 v126, v114, v140
	v_mul_f32_e32 v114, v117, v93
	v_fmac_f32_e32 v123, v118, v140
	v_fmac_f32_e32 v141, v114, v140
	v_cvt_pk_bf16_f32 v116, v123, v124
	v_cvt_pk_bf16_f32 v117, v125, v126
	v_cvt_pk_bf16_f32 v118, v127, v128
	v_cvt_pk_bf16_f32 v119, v129, v141
	global_store_dwordx4 v[138:139], v[116:119], off offset:256
	v_lshlrev_b32_e32 v114, 16, v116
	v_and_b32_e32 v115, 0xffff0000, v116
	v_fmac_f32_e32 v122, v114, v114
	v_lshlrev_b32_e32 v120, 16, v117
	v_fmac_f32_e32 v122, v115, v115
	v_and_b32_e32 v121, 0xffff0000, v117
	v_fmac_f32_e32 v122, v120, v120
	v_lshlrev_b32_e32 v123, 16, v118
	v_fmac_f32_e32 v122, v121, v121
	v_and_b32_e32 v124, 0xffff0000, v118
	v_fmac_f32_e32 v122, v123, v123
	v_lshlrev_b32_e32 v125, 16, v119
	v_fmac_f32_e32 v122, v124, v124
	v_and_b32_e32 v126, 0xffff0000, v119
	v_fmac_f32_e32 v122, v125, v125
	v_fmac_f32_e32 v122, v126, v126
	v_mov_b32_e32 v114, v122
	s_nop 1
	v_permlane16_swap_b32_e32 v114, v122
	s_waitcnt lgkmcnt(0)
	v_add_f32_e32 v114, v122, v114
	v_mov_b32_e32 v115, v114
	s_nop 1
	v_permlane32_swap_b32_e32 v115, v114
	s_and_saveexec_b64 s[54:55], s[44:45]
	s_cbranch_execz .LBB0_493
	s_waitcnt lgkmcnt(0)
	v_add_f32_e32 v114, v114, v115
	ds_write_b32 v228, v114
.LBB0_493:
	s_or_b64 exec, exec, s[54:55]
	v_lshl_add_u32 v114, v196, 2, s64
	ds_read_b32 v124, v114
	s_waitcnt lgkmcnt(1)
	v_lshl_add_u64 v[114:115], s[36:37], 0, v[196:197]
	v_lshlrev_b64 v[114:115], 11, v[114:115]
	v_lshl_add_u64 v[114:115], s[58:59], 0, v[114:115]
	v_lshl_add_u64 v[122:123], v[218:219], 1, v[114:115]
	v_add_co_u32_e32 v116, vcc, 0x40000, v122
	v_lshl_add_u64 v[114:115], v[122:123], 0, s[24:25]
	s_nop 0
	v_addc_co_u32_e32 v117, vcc, 0, v123, vcc
	global_load_dwordx4 v[118:121], v[116:117], off
	s_nop 0
	global_load_dwordx4 v[114:117], v[114:115], off offset:256
	v_lshlrev_b32_e32 v129, 16, v160
	v_mul_f32_e32 v106, v106, v98
	v_and_b32_e32 v126, 0xffff0000, v158
	s_waitcnt lgkmcnt(0)
	v_fmac_f32_e32 v129, v106, v124
	v_mul_f32_e32 v106, v111, v103
	v_and_b32_e32 v138, 0xffff0000, v160
	v_fmac_f32_e32 v126, v106, v124
	v_mul_f32_e32 v106, v107, v99
	v_lshlrev_b32_e32 v127, 16, v159
	v_fmac_f32_e32 v138, v106, v124
	v_mul_f32_e32 v106, v112, v104
	v_lshlrev_b32_e32 v139, 16, v161
	v_fmac_f32_e32 v127, v106, v124
	v_mul_f32_e32 v106, v108, v100
	v_and_b32_e32 v128, 0xffff0000, v159
	v_fmac_f32_e32 v139, v106, v124
	v_mul_f32_e32 v106, v113, v105
	v_lshlrev_b32_e32 v125, 16, v158
	v_and_b32_e32 v140, 0xffff0000, v161
	v_mul_f32_e32 v110, v110, v102
	v_fmac_f32_e32 v128, v106, v124
	v_mul_f32_e32 v106, v109, v101
	v_fmac_f32_e32 v125, v110, v124
	v_fmac_f32_e32 v140, v106, v124
	v_cvt_pk_bf16_f32 v106, v125, v126
	v_cvt_pk_bf16_f32 v107, v127, v128
	v_cvt_pk_bf16_f32 v108, v129, v138
	v_cvt_pk_bf16_f32 v109, v139, v140
	global_store_dwordx4 v[122:123], v[106:109], off
	v_lshlrev_b32_e32 v110, 16, v106
	v_lshlrev_b32_e32 v111, 16, v107
	v_and_b32_e32 v106, 0xffff0000, v106
	v_mul_f32_e32 v106, v106, v106
	v_fmac_f32_e32 v106, v110, v110
	v_and_b32_e32 v107, 0xffff0000, v107
	v_fmac_f32_e32 v106, v111, v111
	v_lshlrev_b32_e32 v112, 16, v108
	v_fmac_f32_e32 v106, v107, v107
	v_and_b32_e32 v108, 0xffff0000, v108
	v_fmac_f32_e32 v106, v112, v112
	v_lshlrev_b32_e32 v111, 16, v156
	v_mul_f32_e32 v82, v82, v90
	v_lshlrev_b32_e32 v113, 16, v109
	v_fmac_f32_e32 v106, v108, v108
	v_and_b32_e32 v108, 0xffff0000, v154
	v_fmac_f32_e32 v111, v82, v124
	v_mul_f32_e32 v82, v87, v95
	v_and_b32_e32 v109, 0xffff0000, v109
	v_fmac_f32_e32 v106, v113, v113
; __device__ __forceinline__ unsigned cvt_pk_bf16(float lo, float hi) { unsigned r; asm volatile("v_cvt_pk_bf16_f32 %0, %1, %2" : "=v"(r) : "v"(lo), "v"(hi)); return r; }
; __device__ __forceinline__ void unpack8(const u32x4 w, float (&v)[8]) { v[0] = bf_lo(w.x); v[1] = bf_hi(w.x); v[2] = bf_lo(w.y); v[3] = bf_hi(w.y); v[4] = bf_lo(w.z); v[5] = bf_hi(w.z); v[6] = bf_lo(w.w); v[7] = bf_hi(w.w); }
;     __device__ __forceinline__ void operator()(const f32x4 (&acc)[2][2][4][2], const Unit& u, int wr, int wc, int fr, int fq) const {
;     ...
;         for (int ai = 0; ai < 2; ++ai)
; #pragma unroll
;             for (int m = 0; m < 4; ++m) { const int rloc = rloc0 + ai * 128 + m * 16; const float rs = S[rloc]; float q2 = 0.f;
;                 u32x4 cur[2]; cur[0] = pre[m][0]; cur[1] = pre[m][1];
;                 if (ai == 0) {
; #pragma unroll
;                     for (int bj = 0; bj < 2; ++bj) pre[m][bj] = *(const u32x4*)(HB + (grow0 + rloc + 128) * DM + colb + bj * 128); }
; #pragma unroll
;                 for (int bj = 0; bj < 2; ++bj) { float h[8]; unpack8(cur[bj], h);
; #pragma unroll
;                     for (int e = 0; e < 4; ++e) { h[e] += acc[ai][bj][m][0][e] * g[bj][0][e] * rs; h[4 + e] += acc[ai][bj][m][1][e] * g[bj][1][e] * rs; }
;                     if (OUT) { float* op = OUT + (grow0 + rloc) * DM + colb + bj * 128; *(f32x4*)op = (f32x4){h[0], h[1], h[2], h[3]}; *(f32x4*)(op + 4) = (f32x4){h[4], h[5], h[6], h[7]}; }
;                     else { u32x4 w; w.x = cvt_pk_bf16(h[0], h[1]); w.y = cvt_pk_bf16(h[2], h[3]); w.z = cvt_pk_bf16(h[4], h[5]); w.w = cvt_pk_bf16(h[6], h[7]);
;                         *(u32x4*)(HB + (grow0 + rloc) * DM + colb + bj * 128) = w; float qv[8]; unpack8(w, qv);
; #pragma unroll
;                         for (int e = 0; e < 8; ++e) q2 += qv[e] * qv[e]; } }
;                 q2 += __shfl_xor(q2, 16); q2 += __shfl_xor(q2, 32);
;                 if (fq == 0) P[rloc * 4 + wc] = q2; }
	v_and_b32_e32 v112, 0xffff0000, v156
	v_fmac_f32_e32 v108, v82, v124
	v_mul_f32_e32 v82, v83, v91
	v_fmac_f32_e32 v106, v109, v109
	v_lshlrev_b32_e32 v109, 16, v155
	v_fmac_f32_e32 v112, v82, v124
	v_mul_f32_e32 v82, v88, v96
	v_lshlrev_b32_e32 v113, 16, v157
	v_fmac_f32_e32 v109, v82, v124
	v_mul_f32_e32 v82, v84, v92
	v_and_b32_e32 v110, 0xffff0000, v155
	v_fmac_f32_e32 v113, v82, v124
	v_mul_f32_e32 v82, v89, v97
	v_lshlrev_b32_e32 v107, 16, v154
	v_and_b32_e32 v125, 0xffff0000, v157
	v_mul_f32_e32 v86, v86, v94
	v_fmac_f32_e32 v110, v82, v124
	v_mul_f32_e32 v82, v85, v93
	v_fmac_f32_e32 v107, v86, v124
	v_fmac_f32_e32 v125, v82, v124
	v_cvt_pk_bf16_f32 v84, v107, v108
	v_cvt_pk_bf16_f32 v85, v109, v110
	v_cvt_pk_bf16_f32 v86, v111, v112
	v_cvt_pk_bf16_f32 v87, v113, v125
	global_store_dwordx4 v[122:123], v[84:87], off offset:256
	v_lshlrev_b32_e32 v82, 16, v84
	v_and_b32_e32 v83, 0xffff0000, v84
	v_fmac_f32_e32 v106, v82, v82
	v_lshlrev_b32_e32 v88, 16, v85
	v_fmac_f32_e32 v106, v83, v83
	v_and_b32_e32 v89, 0xffff0000, v85
	v_fmac_f32_e32 v106, v88, v88
	v_lshlrev_b32_e32 v107, 16, v86
	v_fmac_f32_e32 v106, v89, v89
	v_and_b32_e32 v108, 0xffff0000, v86
	v_fmac_f32_e32 v106, v107, v107
	v_lshlrev_b32_e32 v109, 16, v87
	v_fmac_f32_e32 v106, v108, v108
	v_and_b32_e32 v110, 0xffff0000, v87
	v_fmac_f32_e32 v106, v109, v109
	v_fmac_f32_e32 v106, v110, v110
	v_mov_b32_e32 v82, v106
	s_nop 1
	v_permlane16_swap_b32_e32 v82, v106
	s_waitcnt lgkmcnt(0)
	v_add_f32_e32 v82, v106, v82
	v_mov_b32_e32 v83, v82
	s_nop 1
	v_permlane32_swap_b32_e32 v83, v82
	s_and_saveexec_b64 s[54:55], s[44:45]
	s_cbranch_execz .LBB0_495
	s_waitcnt lgkmcnt(0)
	v_add_f32_e32 v82, v82, v83
	ds_write_b32 v229, v82
.LBB0_495:
	s_or_b64 exec, exec, s[54:55]
	v_lshl_add_u32 v82, v198, 2, s64
	ds_read_b32 v108, v82
	s_waitcnt lgkmcnt(1)
	v_lshl_add_u64 v[82:83], s[36:37], 0, v[198:199]
	v_lshlrev_b64 v[82:83], 11, v[82:83]
	v_lshl_add_u64 v[82:83], s[58:59], 0, v[82:83]
	v_lshl_add_u64 v[106:107], v[218:219], 1, v[82:83]
	v_add_co_u32_e32 v84, vcc, 0x40000, v106
	v_lshl_add_u64 v[82:83], v[106:107], 0, s[24:25]
	s_nop 0
	v_addc_co_u32_e32 v85, vcc, 0, v107, vcc
	global_load_dwordx4 v[86:89], v[84:85], off
	s_nop 0
	global_load_dwordx4 v[82:85], v[82:83], off offset:256
	v_lshlrev_b32_e32 v113, 16, v152
	v_mul_f32_e32 v74, v74, v98
	v_and_b32_e32 v110, 0xffff0000, v150
	s_waitcnt lgkmcnt(0)
	v_fmac_f32_e32 v113, v74, v108
	v_mul_f32_e32 v74, v79, v103
	v_and_b32_e32 v122, 0xffff0000, v152
	v_fmac_f32_e32 v110, v74, v108
	v_mul_f32_e32 v74, v75, v99
	v_lshlrev_b32_e32 v111, 16, v151
	v_fmac_f32_e32 v122, v74, v108
	v_mul_f32_e32 v74, v80, v104
	v_lshlrev_b32_e32 v123, 16, v153
	v_fmac_f32_e32 v111, v74, v108
	v_mul_f32_e32 v74, v76, v100
	v_and_b32_e32 v112, 0xffff0000, v151
	v_fmac_f32_e32 v123, v74, v108
	v_mul_f32_e32 v74, v81, v105
	v_lshlrev_b32_e32 v109, 16, v150
	v_and_b32_e32 v124, 0xffff0000, v153
	v_mul_f32_e32 v78, v78, v102
	v_fmac_f32_e32 v112, v74, v108
	v_mul_f32_e32 v74, v77, v101
	v_fmac_f32_e32 v109, v78, v108
	v_fmac_f32_e32 v124, v74, v108
	v_cvt_pk_bf16_f32 v74, v109, v110
	v_cvt_pk_bf16_f32 v75, v111, v112
	v_cvt_pk_bf16_f32 v76, v113, v122
	v_cvt_pk_bf16_f32 v77, v123, v124
	global_store_dwordx4 v[106:107], v[74:77], off
	v_lshlrev_b32_e32 v78, 16, v74
	v_lshlrev_b32_e32 v79, 16, v75
	v_and_b32_e32 v74, 0xffff0000, v74
	v_mul_f32_e32 v74, v74, v74
	v_fmac_f32_e32 v74, v78, v78
	v_and_b32_e32 v75, 0xffff0000, v75
	v_fmac_f32_e32 v74, v79, v79
	v_lshlrev_b32_e32 v80, 16, v76
	v_fmac_f32_e32 v74, v75, v75
	v_and_b32_e32 v76, 0xffff0000, v76
	v_fmac_f32_e32 v74, v80, v80
	v_lshlrev_b32_e32 v79, 16, v148
	v_mul_f32_e32 v66, v66, v90
	v_lshlrev_b32_e32 v81, 16, v77
	v_fmac_f32_e32 v74, v76, v76
	v_and_b32_e32 v76, 0xffff0000, v146
	v_fmac_f32_e32 v79, v66, v108
	v_mul_f32_e32 v66, v71, v95
	v_and_b32_e32 v77, 0xffff0000, v77
	v_fmac_f32_e32 v74, v81, v81
	v_and_b32_e32 v80, 0xffff0000, v148
	v_fmac_f32_e32 v76, v66, v108
	v_mul_f32_e32 v66, v67, v91
	v_fmac_f32_e32 v74, v77, v77
	v_lshlrev_b32_e32 v77, 16, v147
	v_fmac_f32_e32 v80, v66, v108
	v_mul_f32_e32 v66, v72, v96
	v_lshlrev_b32_e32 v81, 16, v149
	v_fmac_f32_e32 v77, v66, v108
	v_mul_f32_e32 v66, v68, v92
	v_and_b32_e32 v78, 0xffff0000, v147
	v_fmac_f32_e32 v81, v66, v108
	v_mul_f32_e32 v66, v73, v97
	v_lshlrev_b32_e32 v75, 16, v146
	v_and_b32_e32 v109, 0xffff0000, v149
	v_mul_f32_e32 v70, v70, v94
	v_fmac_f32_e32 v78, v66, v108
	v_mul_f32_e32 v66, v69, v93
	v_fmac_f32_e32 v75, v70, v108
	v_fmac_f32_e32 v109, v66, v108
	v_cvt_pk_bf16_f32 v68, v75, v76
	v_cvt_pk_bf16_f32 v69, v77, v78
	v_cvt_pk_bf16_f32 v70, v79, v80
	v_cvt_pk_bf16_f32 v71, v81, v109
	global_store_dwordx4 v[106:107], v[68:71], off offset:256
	v_lshlrev_b32_e32 v66, 16, v68
	v_and_b32_e32 v67, 0xffff0000, v68
	v_fmac_f32_e32 v74, v66, v66
	v_lshlrev_b32_e32 v72, 16, v69
	v_fmac_f32_e32 v74, v67, v67
	v_and_b32_e32 v73, 0xffff0000, v69
	v_fmac_f32_e32 v74, v72, v72
	v_lshlrev_b32_e32 v75, 16, v70
	v_fmac_f32_e32 v74, v73, v73
	v_and_b32_e32 v76, 0xffff0000, v70
	v_fmac_f32_e32 v74, v75, v75
	v_lshlrev_b32_e32 v77, 16, v71
	v_fmac_f32_e32 v74, v76, v76
	v_and_b32_e32 v78, 0xffff0000, v71
	v_fmac_f32_e32 v74, v77, v77
	v_fmac_f32_e32 v74, v78, v78
	v_mov_b32_e32 v66, v74
	s_nop 1
	v_permlane16_swap_b32_e32 v66, v74
	s_waitcnt lgkmcnt(0)
	v_add_f32_e32 v66, v74, v66
	v_mov_b32_e32 v67, v66
	s_nop 1
	v_permlane32_swap_b32_e32 v67, v66
	s_and_saveexec_b64 s[54:55], s[44:45]
	s_cbranch_execz .LBB0_497
	s_waitcnt lgkmcnt(0)
	v_add_f32_e32 v66, v66, v67
	ds_write_b32 v230, v66
; __device__ __forceinline__ unsigned cvt_pk_bf16(float lo, float hi) { unsigned r; asm volatile("v_cvt_pk_bf16_f32 %0, %1, %2" : "=v"(r) : "v"(lo), "v"(hi)); return r; }
; __device__ __forceinline__ void unpack8(const u32x4 w, float (&v)[8]) { v[0] = bf_lo(w.x); v[1] = bf_hi(w.x); v[2] = bf_lo(w.y); v[3] = bf_hi(w.y); v[4] = bf_lo(w.z); v[5] = bf_hi(w.z); v[6] = bf_lo(w.w); v[7] = bf_hi(w.w); }
;     __device__ __forceinline__ void operator()(const f32x4 (&acc)[2][2][4][2], const Unit& u, int wr, int wc, int fr, int fq) const {
;     ...
;         for (int ai = 0; ai < 2; ++ai)
; #pragma unroll
;             for (int m = 0; m < 4; ++m) { const int rloc = rloc0 + ai * 128 + m * 16; const float rs = S[rloc]; float q2 = 0.f;
;                 u32x4 cur[2]; cur[0] = pre[m][0]; cur[1] = pre[m][1];
;                 if (ai == 0) {
; #pragma unroll
;                     for (int bj = 0; bj < 2; ++bj) pre[m][bj] = *(const u32x4*)(HB + (grow0 + rloc + 128) * DM + colb + bj * 128); }
; #pragma unroll
;                 for (int bj = 0; bj < 2; ++bj) { float h[8]; unpack8(cur[bj], h);
; #pragma unroll
;                     for (int e = 0; e < 4; ++e) { h[e] += acc[ai][bj][m][0][e] * g[bj][0][e] * rs; h[4 + e] += acc[ai][bj][m][1][e] * g[bj][1][e] * rs; }
;                     if (OUT) { float* op = OUT + (grow0 + rloc) * DM + colb + bj * 128; *(f32x4*)op = (f32x4){h[0], h[1], h[2], h[3]}; *(f32x4*)(op + 4) = (f32x4){h[4], h[5], h[6], h[7]}; }
;                     else { u32x4 w; w.x = cvt_pk_bf16(h[0], h[1]); w.y = cvt_pk_bf16(h[2], h[3]); w.z = cvt_pk_bf16(h[4], h[5]); w.w = cvt_pk_bf16(h[6], h[7]);
;                         *(u32x4*)(HB + (grow0 + rloc) * DM + colb + bj * 128) = w; float qv[8]; unpack8(w, qv);
; #pragma unroll
;                         for (int e = 0; e < 8; ++e) q2 += qv[e] * qv[e]; } }
;                 q2 += __shfl_xor(q2, 16); q2 += __shfl_xor(q2, 32);
;                 if (fq == 0) P[rloc * 4 + wc] = q2; }
.LBB0_497:
	s_or_b64 exec, exec, s[54:55]
	v_lshl_add_u32 v66, v200, 2, s64
	ds_read_b32 v68, v66
	s_waitcnt vmcnt(8)
	v_lshlrev_b32_e32 v73, 16, v184
	v_mul_f32_e32 v58, v58, v98
	v_and_b32_e32 v70, 0xffff0000, v182
	v_and_b32_e32 v74, 0xffff0000, v184
	s_waitcnt lgkmcnt(0)
	v_fmac_f32_e32 v73, v58, v68
	v_mul_f32_e32 v58, v63, v103
	v_fmac_f32_e32 v70, v58, v68
	v_mul_f32_e32 v58, v59, v99
	v_lshlrev_b32_e32 v71, 16, v183
	v_fmac_f32_e32 v74, v58, v68
	v_mul_f32_e32 v58, v64, v104
	v_lshl_add_u64 v[66:67], s[36:37], 0, v[200:201]
	v_lshlrev_b32_e32 v75, 16, v185
	v_fmac_f32_e32 v71, v58, v68
	v_mul_f32_e32 v58, v60, v100
	v_lshlrev_b64 v[66:67], 11, v[66:67]
	v_lshlrev_b32_e32 v69, 16, v182
	v_and_b32_e32 v72, 0xffff0000, v183
	v_mul_f32_e32 v62, v62, v102
	v_fmac_f32_e32 v75, v58, v68
	v_mul_f32_e32 v58, v65, v105
	v_and_b32_e32 v76, 0xffff0000, v185
	v_fmac_f32_e32 v69, v62, v68
	v_fmac_f32_e32 v72, v58, v68
	v_mul_f32_e32 v58, v61, v101
	v_lshl_add_u64 v[62:63], s[58:59], 0, v[66:67]
	v_fmac_f32_e32 v76, v58, v68
	v_cvt_pk_bf16_f32 v58, v69, v70
	v_lshl_add_u64 v[62:63], v[218:219], 1, v[62:63]
	v_cvt_pk_bf16_f32 v59, v71, v72
	v_cvt_pk_bf16_f32 v60, v73, v74
	v_cvt_pk_bf16_f32 v61, v75, v76
	global_store_dwordx4 v[62:63], v[58:61], off
	v_lshlrev_b32_e32 v64, 16, v58
	v_lshlrev_b32_e32 v65, 16, v59
	v_and_b32_e32 v58, 0xffff0000, v58
	v_mul_f32_e32 v58, v58, v58
	v_fmac_f32_e32 v58, v64, v64
	v_and_b32_e32 v59, 0xffff0000, v59
	v_fmac_f32_e32 v58, v65, v65
	v_lshlrev_b32_e32 v66, 16, v60
	v_fmac_f32_e32 v58, v59, v59
	v_and_b32_e32 v60, 0xffff0000, v60
	v_fmac_f32_e32 v58, v66, v66
	v_lshlrev_b32_e32 v65, 16, v176
	v_mul_f32_e32 v50, v50, v90
	v_lshlrev_b32_e32 v67, 16, v61
	v_fmac_f32_e32 v58, v60, v60
	v_and_b32_e32 v60, 0xffff0000, v174
	v_fmac_f32_e32 v65, v50, v68
	v_mul_f32_e32 v50, v55, v95
	v_and_b32_e32 v61, 0xffff0000, v61
	v_fmac_f32_e32 v58, v67, v67
	v_and_b32_e32 v66, 0xffff0000, v176
	v_fmac_f32_e32 v60, v50, v68
	v_mul_f32_e32 v50, v51, v91
	v_fmac_f32_e32 v58, v61, v61
	v_lshlrev_b32_e32 v61, 16, v175
	v_fmac_f32_e32 v66, v50, v68
	v_mul_f32_e32 v50, v56, v96
	v_lshlrev_b32_e32 v67, 16, v177
	v_fmac_f32_e32 v61, v50, v68
	v_mul_f32_e32 v50, v52, v92
	v_and_b32_e32 v64, 0xffff0000, v175
	v_fmac_f32_e32 v67, v50, v68
	v_mul_f32_e32 v50, v57, v97
	v_lshlrev_b32_e32 v59, 16, v174
	v_and_b32_e32 v69, 0xffff0000, v177
	v_mul_f32_e32 v54, v54, v94
	v_fmac_f32_e32 v64, v50, v68
	v_mul_f32_e32 v50, v53, v93
	v_fmac_f32_e32 v59, v54, v68
	v_fmac_f32_e32 v69, v50, v68
	v_cvt_pk_bf16_f32 v52, v59, v60
	v_cvt_pk_bf16_f32 v53, v61, v64
	v_cvt_pk_bf16_f32 v54, v65, v66
	v_cvt_pk_bf16_f32 v55, v67, v69
	global_store_dwordx4 v[62:63], v[52:55], off offset:256
	v_lshlrev_b32_e32 v50, 16, v52
	v_and_b32_e32 v51, 0xffff0000, v52
	v_fmac_f32_e32 v58, v50, v50
	v_lshlrev_b32_e32 v56, 16, v53
	v_fmac_f32_e32 v58, v51, v51
	v_and_b32_e32 v57, 0xffff0000, v53
	v_fmac_f32_e32 v58, v56, v56
	v_lshlrev_b32_e32 v59, 16, v54
	v_fmac_f32_e32 v58, v57, v57
	v_and_b32_e32 v60, 0xffff0000, v54
	v_fmac_f32_e32 v58, v59, v59
	v_lshlrev_b32_e32 v61, 16, v55
	v_fmac_f32_e32 v58, v60, v60
	v_and_b32_e32 v64, 0xffff0000, v55
	v_fmac_f32_e32 v58, v61, v61
	v_fmac_f32_e32 v58, v64, v64
	v_mov_b32_e32 v50, v58
	s_nop 1
	v_permlane16_swap_b32_e32 v50, v58
	s_waitcnt lgkmcnt(0)
	v_add_f32_e32 v50, v58, v50
	v_mov_b32_e32 v51, v50
	s_nop 1
	v_permlane32_swap_b32_e32 v51, v50
	s_and_saveexec_b64 s[54:55], s[44:45]
	s_cbranch_execz .LBB0_499
	s_waitcnt lgkmcnt(0)
	v_add_f32_e32 v50, v50, v51
	ds_write_b32 v231, v50
.LBB0_499:
	s_or_b64 exec, exec, s[54:55]
	v_lshl_add_u32 v50, v208, 2, s64
	ds_read_b32 v52, v50
	s_waitcnt vmcnt(13)
	v_lshlrev_b32_e32 v57, 16, v136
	v_mul_f32_e32 v42, v42, v98
	v_and_b32_e32 v54, 0xffff0000, v134
	v_and_b32_e32 v58, 0xffff0000, v136
	s_waitcnt lgkmcnt(0)
	v_fmac_f32_e32 v57, v42, v52
	v_mul_f32_e32 v42, v47, v103
	v_fmac_f32_e32 v54, v42, v52
	v_mul_f32_e32 v42, v43, v99
	v_lshlrev_b32_e32 v55, 16, v135
	v_fmac_f32_e32 v58, v42, v52
	v_mul_f32_e32 v42, v48, v104
	v_lshl_add_u64 v[50:51], s[36:37], 0, v[208:209]
	v_lshlrev_b32_e32 v59, 16, v137
	v_fmac_f32_e32 v55, v42, v52
	v_mul_f32_e32 v42, v44, v100
	v_lshlrev_b64 v[50:51], 11, v[50:51]
	v_lshlrev_b32_e32 v53, 16, v134
	v_and_b32_e32 v56, 0xffff0000, v135
	v_mul_f32_e32 v46, v46, v102
	v_fmac_f32_e32 v59, v42, v52
	v_mul_f32_e32 v42, v49, v105
	v_and_b32_e32 v60, 0xffff0000, v137
	v_fmac_f32_e32 v53, v46, v52
	v_fmac_f32_e32 v56, v42, v52
	v_mul_f32_e32 v42, v45, v101
	v_lshl_add_u64 v[46:47], s[58:59], 0, v[50:51]
	v_fmac_f32_e32 v60, v42, v52
	v_cvt_pk_bf16_f32 v42, v53, v54
	v_lshl_add_u64 v[46:47], v[218:219], 1, v[46:47]
	v_cvt_pk_bf16_f32 v43, v55, v56
	v_cvt_pk_bf16_f32 v44, v57, v58
	v_cvt_pk_bf16_f32 v45, v59, v60
	global_store_dwordx4 v[46:47], v[42:45], off
	v_lshlrev_b32_e32 v48, 16, v42
	v_lshlrev_b32_e32 v49, 16, v43
	v_and_b32_e32 v42, 0xffff0000, v42
	v_mul_f32_e32 v42, v42, v42
	v_fmac_f32_e32 v42, v48, v48
	v_and_b32_e32 v43, 0xffff0000, v43
	v_fmac_f32_e32 v42, v49, v49
	v_lshlrev_b32_e32 v50, 16, v44
	v_fmac_f32_e32 v42, v43, v43
	v_and_b32_e32 v44, 0xffff0000, v44
	v_fmac_f32_e32 v42, v50, v50
	s_waitcnt vmcnt(13)
; __device__ __forceinline__ unsigned cvt_pk_bf16(float lo, float hi) { unsigned r; asm volatile("v_cvt_pk_bf16_f32 %0, %1, %2" : "=v"(r) : "v"(lo), "v"(hi)); return r; }
; __device__ __forceinline__ void unpack8(const u32x4 w, float (&v)[8]) { v[0] = bf_lo(w.x); v[1] = bf_hi(w.x); v[2] = bf_lo(w.y); v[3] = bf_hi(w.y); v[4] = bf_lo(w.z); v[5] = bf_hi(w.z); v[6] = bf_lo(w.w); v[7] = bf_hi(w.w); }
;     __device__ __forceinline__ void operator()(const f32x4 (&acc)[2][2][4][2], const Unit& u, int wr, int wc, int fr, int fq) const {
;     ...
;         for (int ai = 0; ai < 2; ++ai)
; #pragma unroll
;             for (int m = 0; m < 4; ++m) { const int rloc = rloc0 + ai * 128 + m * 16; const float rs = S[rloc]; float q2 = 0.f;
;                 u32x4 cur[2]; cur[0] = pre[m][0]; cur[1] = pre[m][1];
;                 if (ai == 0) {
; #pragma unroll
;                     for (int bj = 0; bj < 2; ++bj) pre[m][bj] = *(const u32x4*)(HB + (grow0 + rloc + 128) * DM + colb + bj * 128); }
; #pragma unroll
;                 for (int bj = 0; bj < 2; ++bj) { float h[8]; unpack8(cur[bj], h);
; #pragma unroll
;                     for (int e = 0; e < 4; ++e) { h[e] += acc[ai][bj][m][0][e] * g[bj][0][e] * rs; h[4 + e] += acc[ai][bj][m][1][e] * g[bj][1][e] * rs; }
;                     if (OUT) { float* op = OUT + (grow0 + rloc) * DM + colb + bj * 128; *(f32x4*)op = (f32x4){h[0], h[1], h[2], h[3]}; *(f32x4*)(op + 4) = (f32x4){h[4], h[5], h[6], h[7]}; }
;                     else { u32x4 w; w.x = cvt_pk_bf16(h[0], h[1]); w.y = cvt_pk_bf16(h[2], h[3]); w.z = cvt_pk_bf16(h[4], h[5]); w.w = cvt_pk_bf16(h[6], h[7]);
;                         *(u32x4*)(HB + (grow0 + rloc) * DM + colb + bj * 128) = w; float qv[8]; unpack8(w, qv);
; #pragma unroll
;                         for (int e = 0; e < 8; ++e) q2 += qv[e] * qv[e]; } }
;                 q2 += __shfl_xor(q2, 16); q2 += __shfl_xor(q2, 32);
;                 if (fq == 0) P[rloc * 4 + wc] = q2; }
	v_lshlrev_b32_e32 v49, 16, v132
	v_mul_f32_e32 v34, v34, v90
	v_lshlrev_b32_e32 v51, 16, v45
	v_fmac_f32_e32 v42, v44, v44
	v_and_b32_e32 v44, 0xffff0000, v130
	v_fmac_f32_e32 v49, v34, v52
	v_mul_f32_e32 v34, v39, v95
	v_and_b32_e32 v45, 0xffff0000, v45
	v_fmac_f32_e32 v42, v51, v51
	v_and_b32_e32 v50, 0xffff0000, v132
	v_fmac_f32_e32 v44, v34, v52
	v_mul_f32_e32 v34, v35, v91
	v_fmac_f32_e32 v42, v45, v45
	v_lshlrev_b32_e32 v45, 16, v131
	v_fmac_f32_e32 v50, v34, v52
	v_mul_f32_e32 v34, v40, v96
	v_lshlrev_b32_e32 v51, 16, v133
	v_fmac_f32_e32 v45, v34, v52
	v_mul_f32_e32 v34, v36, v92
	v_and_b32_e32 v48, 0xffff0000, v131
	v_fmac_f32_e32 v51, v34, v52
	v_mul_f32_e32 v34, v41, v97
	v_lshlrev_b32_e32 v43, 16, v130
	v_and_b32_e32 v53, 0xffff0000, v133
	v_mul_f32_e32 v38, v38, v94
	v_fmac_f32_e32 v48, v34, v52
	v_mul_f32_e32 v34, v37, v93
	v_fmac_f32_e32 v43, v38, v52
	v_fmac_f32_e32 v53, v34, v52
	v_cvt_pk_bf16_f32 v36, v43, v44
	v_cvt_pk_bf16_f32 v37, v45, v48
	v_cvt_pk_bf16_f32 v38, v49, v50
	v_cvt_pk_bf16_f32 v39, v51, v53
	global_store_dwordx4 v[46:47], v[36:39], off offset:256
	v_lshlrev_b32_e32 v34, 16, v36
	v_and_b32_e32 v35, 0xffff0000, v36
	v_fmac_f32_e32 v42, v34, v34
	v_lshlrev_b32_e32 v40, 16, v37
	v_fmac_f32_e32 v42, v35, v35
	v_and_b32_e32 v41, 0xffff0000, v37
	v_fmac_f32_e32 v42, v40, v40
	v_lshlrev_b32_e32 v43, 16, v38
	v_fmac_f32_e32 v42, v41, v41
	v_and_b32_e32 v44, 0xffff0000, v38
	v_fmac_f32_e32 v42, v43, v43
	v_lshlrev_b32_e32 v45, 16, v39
	v_fmac_f32_e32 v42, v44, v44
	v_and_b32_e32 v48, 0xffff0000, v39
	v_fmac_f32_e32 v42, v45, v45
	v_fmac_f32_e32 v42, v48, v48
	v_mov_b32_e32 v34, v42
	s_nop 1
	v_permlane16_swap_b32_e32 v34, v42
	s_waitcnt lgkmcnt(0)
	v_add_f32_e32 v34, v42, v34
	v_mov_b32_e32 v35, v34
	s_nop 1
	v_permlane32_swap_b32_e32 v35, v34
	s_and_saveexec_b64 s[54:55], s[44:45]
	s_cbranch_execz .LBB0_501
	s_waitcnt lgkmcnt(0)
	v_add_f32_e32 v34, v34, v35
	ds_write_b32 v232, v34
.LBB0_501:
	s_or_b64 exec, exec, s[54:55]
	v_lshl_add_u32 v34, v210, 2, s64
	ds_read_b32 v36, v34
	s_waitcnt vmcnt(11)
	v_lshlrev_b32_e32 v41, 16, v120
	v_mul_f32_e32 v26, v26, v98
	v_and_b32_e32 v38, 0xffff0000, v118
	v_and_b32_e32 v42, 0xffff0000, v120
	s_waitcnt lgkmcnt(0)
	v_fmac_f32_e32 v41, v26, v36
	v_mul_f32_e32 v26, v31, v103
	v_fmac_f32_e32 v38, v26, v36
	v_mul_f32_e32 v26, v27, v99
	v_lshlrev_b32_e32 v39, 16, v119
	v_fmac_f32_e32 v42, v26, v36
	v_mul_f32_e32 v26, v32, v104
	v_lshl_add_u64 v[34:35], s[36:37], 0, v[210:211]
	v_lshlrev_b32_e32 v43, 16, v121
	v_fmac_f32_e32 v39, v26, v36
	v_mul_f32_e32 v26, v28, v100
	v_lshlrev_b64 v[34:35], 11, v[34:35]
	v_lshlrev_b32_e32 v37, 16, v118
	v_and_b32_e32 v40, 0xffff0000, v119
	v_mul_f32_e32 v30, v30, v102
	v_fmac_f32_e32 v43, v26, v36
	v_mul_f32_e32 v26, v33, v105
	v_and_b32_e32 v44, 0xffff0000, v121
	v_fmac_f32_e32 v37, v30, v36
	v_fmac_f32_e32 v40, v26, v36
	v_mul_f32_e32 v26, v29, v101
	v_lshl_add_u64 v[30:31], s[58:59], 0, v[34:35]
	v_fmac_f32_e32 v44, v26, v36
	v_cvt_pk_bf16_f32 v26, v37, v38
	v_lshl_add_u64 v[30:31], v[218:219], 1, v[30:31]
	v_cvt_pk_bf16_f32 v27, v39, v40
	v_cvt_pk_bf16_f32 v28, v41, v42
	v_cvt_pk_bf16_f32 v29, v43, v44
	global_store_dwordx4 v[30:31], v[26:29], off
	v_lshlrev_b32_e32 v32, 16, v26
	v_lshlrev_b32_e32 v33, 16, v27
	v_and_b32_e32 v26, 0xffff0000, v26
	v_mul_f32_e32 v26, v26, v26
	v_fmac_f32_e32 v26, v32, v32
	v_and_b32_e32 v27, 0xffff0000, v27
	v_fmac_f32_e32 v26, v33, v33
	v_lshlrev_b32_e32 v34, 16, v28
	v_fmac_f32_e32 v26, v27, v27
	v_and_b32_e32 v28, 0xffff0000, v28
	v_fmac_f32_e32 v26, v34, v34
	s_waitcnt vmcnt(11)
	v_lshlrev_b32_e32 v33, 16, v116
	v_mul_f32_e32 v18, v18, v90
	v_lshlrev_b32_e32 v35, 16, v29
	v_fmac_f32_e32 v26, v28, v28
	v_and_b32_e32 v28, 0xffff0000, v114
	v_fmac_f32_e32 v33, v18, v36
	v_mul_f32_e32 v18, v23, v95
	v_and_b32_e32 v29, 0xffff0000, v29
	v_fmac_f32_e32 v26, v35, v35
	v_and_b32_e32 v34, 0xffff0000, v116
	v_fmac_f32_e32 v28, v18, v36
	v_mul_f32_e32 v18, v19, v91
	v_fmac_f32_e32 v26, v29, v29
	v_lshlrev_b32_e32 v29, 16, v115
	v_fmac_f32_e32 v34, v18, v36
	v_mul_f32_e32 v18, v24, v96
	v_lshlrev_b32_e32 v35, 16, v117
	v_fmac_f32_e32 v29, v18, v36
	v_mul_f32_e32 v18, v20, v92
	v_and_b32_e32 v32, 0xffff0000, v115
	v_fmac_f32_e32 v35, v18, v36
	v_mul_f32_e32 v18, v25, v97
	v_lshlrev_b32_e32 v27, 16, v114
	v_and_b32_e32 v37, 0xffff0000, v117
	v_mul_f32_e32 v22, v22, v94
	v_fmac_f32_e32 v32, v18, v36
	v_mul_f32_e32 v18, v21, v93
	v_fmac_f32_e32 v27, v22, v36
	v_fmac_f32_e32 v37, v18, v36
	v_cvt_pk_bf16_f32 v20, v27, v28
	v_cvt_pk_bf16_f32 v21, v29, v32
	v_cvt_pk_bf16_f32 v22, v33, v34
	v_cvt_pk_bf16_f32 v23, v35, v37
	global_store_dwordx4 v[30:31], v[20:23], off offset:256
	v_lshlrev_b32_e32 v18, 16, v20
	v_and_b32_e32 v19, 0xffff0000, v20
	v_fmac_f32_e32 v26, v18, v18
	v_lshlrev_b32_e32 v24, 16, v21
	v_fmac_f32_e32 v26, v19, v19
	v_and_b32_e32 v25, 0xffff0000, v21
	v_fmac_f32_e32 v26, v24, v24
	v_lshlrev_b32_e32 v27, 16, v22
	v_fmac_f32_e32 v26, v25, v25
	v_and_b32_e32 v28, 0xffff0000, v22
	v_fmac_f32_e32 v26, v27, v27
	v_lshlrev_b32_e32 v29, 16, v23
	v_fmac_f32_e32 v26, v28, v28
	v_and_b32_e32 v32, 0xffff0000, v23
	v_fmac_f32_e32 v26, v29, v29
	v_fmac_f32_e32 v26, v32, v32
	v_mov_b32_e32 v18, v26
	s_nop 1
	v_permlane16_swap_b32_e32 v18, v26
	s_waitcnt lgkmcnt(0)
	v_add_f32_e32 v18, v26, v18
	v_mov_b32_e32 v19, v18
	s_nop 1
	v_permlane32_swap_b32_e32 v19, v18
	s_and_saveexec_b64 s[54:55], s[44:45]
	s_cbranch_execz .LBB0_503
	s_waitcnt lgkmcnt(0)
	v_add_f32_e32 v18, v18, v19
	ds_write_b32 v233, v18
; __device__ __forceinline__ unsigned cvt_pk_bf16(float lo, float hi) { unsigned r; asm volatile("v_cvt_pk_bf16_f32 %0, %1, %2" : "=v"(r) : "v"(lo), "v"(hi)); return r; }
; __device__ __forceinline__ void unpack8(const u32x4 w, float (&v)[8]) { v[0] = bf_lo(w.x); v[1] = bf_hi(w.x); v[2] = bf_lo(w.y); v[3] = bf_hi(w.y); v[4] = bf_lo(w.z); v[5] = bf_hi(w.z); v[6] = bf_lo(w.w); v[7] = bf_hi(w.w); }
;     __device__ __forceinline__ void operator()(const f32x4 (&acc)[2][2][4][2], const Unit& u, int wr, int wc, int fr, int fq) const {
;     ...
;         for (int ai = 0; ai < 2; ++ai)
; #pragma unroll
;             for (int m = 0; m < 4; ++m) { const int rloc = rloc0 + ai * 128 + m * 16; const float rs = S[rloc]; float q2 = 0.f;
;                 u32x4 cur[2]; cur[0] = pre[m][0]; cur[1] = pre[m][1];
;                 if (ai == 0) {
; #pragma unroll
;                     for (int bj = 0; bj < 2; ++bj) pre[m][bj] = *(const u32x4*)(HB + (grow0 + rloc + 128) * DM + colb + bj * 128); }
; #pragma unroll
;                 for (int bj = 0; bj < 2; ++bj) { float h[8]; unpack8(cur[bj], h);
; #pragma unroll
;                     for (int e = 0; e < 4; ++e) { h[e] += acc[ai][bj][m][0][e] * g[bj][0][e] * rs; h[4 + e] += acc[ai][bj][m][1][e] * g[bj][1][e] * rs; }
;                     if (OUT) { float* op = OUT + (grow0 + rloc) * DM + colb + bj * 128; *(f32x4*)op = (f32x4){h[0], h[1], h[2], h[3]}; *(f32x4*)(op + 4) = (f32x4){h[4], h[5], h[6], h[7]}; }
;                     else { u32x4 w; w.x = cvt_pk_bf16(h[0], h[1]); w.y = cvt_pk_bf16(h[2], h[3]); w.z = cvt_pk_bf16(h[4], h[5]); w.w = cvt_pk_bf16(h[6], h[7]);
;                         *(u32x4*)(HB + (grow0 + rloc) * DM + colb + bj * 128) = w; float qv[8]; unpack8(w, qv);
; #pragma unroll
;                         for (int e = 0; e < 8; ++e) q2 += qv[e] * qv[e]; } }
;                 q2 += __shfl_xor(q2, 16); q2 += __shfl_xor(q2, 32);
;                 if (fq == 0) P[rloc * 4 + wc] = q2; }
.LBB0_503:
	s_or_b64 exec, exec, s[54:55]
	ds_read_b32 v20, v226
	s_waitcnt vmcnt(9)
	v_lshlrev_b32_e32 v25, 16, v88
	v_mul_f32_e32 v10, v10, v98
	v_and_b32_e32 v22, 0xffff0000, v86
	v_and_b32_e32 v26, 0xffff0000, v88
	s_waitcnt lgkmcnt(0)
	v_fmac_f32_e32 v25, v10, v20
	v_mul_f32_e32 v10, v15, v103
	v_fmac_f32_e32 v22, v10, v20
	v_mul_f32_e32 v10, v11, v99
	v_lshlrev_b32_e32 v23, 16, v87
	v_fmac_f32_e32 v26, v10, v20
	v_mul_f32_e32 v10, v16, v104
	v_lshl_add_u64 v[18:19], s[36:37], 0, v[212:213]
	v_lshlrev_b32_e32 v27, 16, v89
	v_fmac_f32_e32 v23, v10, v20
	v_mul_f32_e32 v10, v12, v100
	v_lshlrev_b64 v[18:19], 11, v[18:19]
	v_lshlrev_b32_e32 v21, 16, v86
	v_and_b32_e32 v24, 0xffff0000, v87
	v_mul_f32_e32 v14, v14, v102
	v_fmac_f32_e32 v27, v10, v20
	v_mul_f32_e32 v10, v17, v105
	v_and_b32_e32 v28, 0xffff0000, v89
	v_fmac_f32_e32 v21, v14, v20
	v_fmac_f32_e32 v24, v10, v20
	v_mul_f32_e32 v10, v13, v101
	v_lshl_add_u64 v[14:15], s[58:59], 0, v[18:19]
	v_fmac_f32_e32 v28, v10, v20
	v_cvt_pk_bf16_f32 v10, v21, v22
	v_lshl_add_u64 v[14:15], v[218:219], 1, v[14:15]
	v_cvt_pk_bf16_f32 v11, v23, v24
	v_cvt_pk_bf16_f32 v12, v25, v26
	v_cvt_pk_bf16_f32 v13, v27, v28
	global_store_dwordx4 v[14:15], v[10:13], off
	v_lshlrev_b32_e32 v16, 16, v10
	v_lshlrev_b32_e32 v17, 16, v11
	v_and_b32_e32 v10, 0xffff0000, v10
	v_mul_f32_e32 v10, v10, v10
	v_fmac_f32_e32 v10, v16, v16
	v_and_b32_e32 v11, 0xffff0000, v11
	v_fmac_f32_e32 v10, v17, v17
	v_lshlrev_b32_e32 v18, 16, v12
	v_fmac_f32_e32 v10, v11, v11
	v_and_b32_e32 v12, 0xffff0000, v12
	v_fmac_f32_e32 v10, v18, v18
	s_waitcnt vmcnt(9)
	v_lshlrev_b32_e32 v17, 16, v84
	v_mul_f32_e32 v2, v2, v90
	v_lshlrev_b32_e32 v19, 16, v13
	v_fmac_f32_e32 v10, v12, v12
	v_and_b32_e32 v12, 0xffff0000, v82
	v_fmac_f32_e32 v17, v2, v20
	v_mul_f32_e32 v2, v7, v95
	v_and_b32_e32 v13, 0xffff0000, v13
	v_fmac_f32_e32 v10, v19, v19
	v_and_b32_e32 v18, 0xffff0000, v84
	v_fmac_f32_e32 v12, v2, v20
	v_mul_f32_e32 v2, v3, v91
	v_fmac_f32_e32 v10, v13, v13
	v_lshlrev_b32_e32 v13, 16, v83
	v_fmac_f32_e32 v18, v2, v20
	v_mul_f32_e32 v2, v8, v96
	v_lshlrev_b32_e32 v19, 16, v85
	v_fmac_f32_e32 v13, v2, v20
	v_mul_f32_e32 v2, v4, v92
	v_and_b32_e32 v16, 0xffff0000, v83
	v_fmac_f32_e32 v19, v2, v20
	v_mul_f32_e32 v2, v9, v97
	v_lshlrev_b32_e32 v11, 16, v82
	v_and_b32_e32 v21, 0xffff0000, v85
	v_mul_f32_e32 v6, v6, v94
	v_fmac_f32_e32 v16, v2, v20
	v_mul_f32_e32 v2, v5, v93
	v_fmac_f32_e32 v11, v6, v20
	v_fmac_f32_e32 v21, v2, v20
	v_cvt_pk_bf16_f32 v4, v11, v12
	v_cvt_pk_bf16_f32 v5, v13, v16
	v_cvt_pk_bf16_f32 v6, v17, v18
	v_cvt_pk_bf16_f32 v7, v19, v21
	global_store_dwordx4 v[14:15], v[4:7], off offset:256
	v_lshlrev_b32_e32 v2, 16, v4
	v_and_b32_e32 v3, 0xffff0000, v4
	v_fmac_f32_e32 v10, v2, v2
	v_lshlrev_b32_e32 v8, 16, v5
	v_fmac_f32_e32 v10, v3, v3
	v_and_b32_e32 v9, 0xffff0000, v5
	v_fmac_f32_e32 v10, v8, v8
	v_lshlrev_b32_e32 v11, 16, v6
	v_fmac_f32_e32 v10, v9, v9
	v_and_b32_e32 v12, 0xffff0000, v6
	v_fmac_f32_e32 v10, v11, v11
	v_lshlrev_b32_e32 v13, 16, v7
	v_fmac_f32_e32 v10, v12, v12
	v_and_b32_e32 v16, 0xffff0000, v7
	v_fmac_f32_e32 v10, v13, v13
	v_fmac_f32_e32 v10, v16, v16
	v_mov_b32_e32 v2, v10
	s_nop 1
	v_permlane16_swap_b32_e32 v2, v10
	s_waitcnt lgkmcnt(0)
	v_add_f32_e32 v2, v10, v2
	v_mov_b32_e32 v3, v2
	s_nop 1
	v_permlane32_swap_b32_e32 v3, v2
	s_and_saveexec_b64 s[54:55], s[44:45]
	s_cbranch_execz .LBB0_505
	s_waitcnt lgkmcnt(0)
	v_add_f32_e32 v2, v2, v3
	ds_write_b32 v238, v2

;     __device__ __forceinline__ void operator()(const f32x4 (&acc)[2][2][4][2], const Unit& u, int wr, int wc, int fr, int fq) const {
;     ...
;         f32x4 g[2][2];
; #pragma unroll
;         for (int bj = 0; bj < 2; ++bj) { g[bj][0] = *(const f32x4*)(ga + colb + bj * 128); g[bj][1] = *(const f32x4*)(ga + colb + bj * 128 + 4); }
;         u32x4 pre[4][2];
; #pragma unroll
;         for (int m = 0; m < 4; ++m)
; #pragma unroll
;             for (int bj = 0; bj < 2; ++bj) pre[m][bj] = *(const u32x4*)(HB + (grow0 + rloc0 + m * 16) * DM + colb + bj * 128);
; #pragma unroll
;         for (int ai = 0; ai < 2; ++ai)
; #pragma unroll
;             for (int m = 0; m < 4; ++m) { float q = 0.f;
; #pragma unroll
;                 for (int bj = 0; bj < 2; ++bj)
; #pragma unroll
;                     for (int n = 0; n < 2; ++n) { const f32x4 x = acc[ai][bj][m][n]; q += (x[0] * x[0] + x[1] * x[1]) + (x[2] * x[2] + x[3] * x[3]); }
;                 q += __shfl_xor(q, 16); q += __shfl_xor(q, 32);
;                 if (fq == 0) P[(rloc0 + ai * 128 + m * 16) * 4 + wc] = q; }
.LBB0_1140:
	s_ashr_i32 s9, s8, 31
	v_lshl_or_b32 v218, s38, 8, v223
	s_lshl_b64 s[0:1], s[8:9], 8
	v_ashrrev_i32_e32 v219, 31, v218
	v_lshl_add_u64 v[146:147], s[0:1], 0, v[192:193]
	v_lshl_add_u64 v[148:149], v[218:219], 1, s[58:59]
	v_lshlrev_b64 v[174:175], 11, v[146:147]
	v_lshl_add_u64 v[146:147], v[148:149], 0, v[174:175]
	v_add_co_u32_e32 v148, vcc, s72, v146
	v_lshl_add_u64 v[94:95], v[218:219], 2, s[18:19]
	s_nop 0
	v_addc_co_u32_e32 v149, vcc, 0, v147, vcc
	s_mov_b32 s14, 0x10000
	global_load_dwordx4 v[98:101], v[94:95], off offset:16
	global_load_dwordx4 v[102:105], v[94:95], off
	global_load_dwordx4 v[90:93], v[94:95], off offset:528
	s_nop 0
	global_load_dwordx4 v[94:97], v[94:95], off offset:512
	s_nop 0
	global_load_dwordx4 v[178:181], v[146:147], off
	global_load_dwordx4 v[170:173], v[146:147], off offset:256
	global_load_dwordx4 v[166:169], v[148:149], off
	global_load_dwordx4 v[162:165], v[148:149], off offset:256
	v_add_co_u32_e32 v148, vcc, s14, v146
	s_mov_b32 s14, 0x18000
	s_nop 0
	v_addc_co_u32_e32 v149, vcc, 0, v147, vcc
	v_add_co_u32_e32 v146, vcc, s14, v146
	global_load_dwordx4 v[158:161], v[148:149], off
	global_load_dwordx4 v[154:157], v[148:149], off offset:256
	v_addc_co_u32_e32 v147, vcc, 0, v147, vcc
	global_load_dwordx4 v[150:153], v[146:147], off
	s_nop 0
	global_load_dwordx4 v[146:149], v[146:147], off offset:256
	v_and_b32_e32 v177, 64, v237
	v_xor_b32_e32 v176, 16, v237
	v_add_u32_e32 v177, 64, v177
	v_cmp_lt_i32_e32 vcc, v176, v177
	v_mul_f32_e32 v182, v145, v145
	v_fmac_f32_e32 v182, v144, v144
	v_cndmask_b32_e32 v176, v237, v176, vcc
	v_lshlrev_b32_e32 v239, 2, v176
	v_mul_f32_e32 v176, v143, v143
	v_fmac_f32_e32 v176, v142, v142
	v_add_f32_e32 v176, v176, v182
	v_mul_f32_e32 v182, v139, v139
	v_mul_f32_e32 v183, v141, v141
	v_fmac_f32_e32 v182, v138, v138
	v_fmac_f32_e32 v183, v140, v140
	v_add_f32_e32 v182, v182, v183
	v_add_f32_e32 v176, v176, v182
	v_mul_f32_e32 v182, v135, v135
	v_mul_f32_e32 v183, v137, v137
	v_fmac_f32_e32 v182, v134, v134
	v_fmac_f32_e32 v183, v136, v136
	v_add_f32_e32 v182, v182, v183
	v_add_f32_e32 v176, v176, v182
	v_mul_f32_e32 v182, v131, v131
	v_mul_f32_e32 v183, v133, v133
	v_fmac_f32_e32 v182, v130, v130
	v_fmac_f32_e32 v183, v132, v132
	v_add_f32_e32 v182, v182, v183
	v_add_f32_e32 v176, v176, v182
	v_mov_b32_e32 v182, v176
	s_nop 1
	v_permlane16_swap_b32_e32 v182, v176
	v_xor_b32_e32 v183, 32, v237
	v_cmp_lt_i32_e32 vcc, v183, v177
	s_waitcnt lgkmcnt(0)
	v_add_f32_e32 v176, v176, v182
	v_cndmask_b32_e32 v177, v237, v183, vcc
	v_lshlrev_b32_e32 v240, 2, v177
	v_mov_b32_e32 v177, v176
	s_nop 1
	v_permlane32_swap_b32_e32 v177, v176
	s_and_saveexec_b64 s[14:15], s[42:43]
	s_cbranch_execz .LBB0_1142
	s_waitcnt lgkmcnt(0)
	v_add_f32_e32 v176, v176, v177
	ds_write_b32 v224, v176
.LBB0_1142:
	s_or_b64 exec, exec, s[14:15]
	v_mul_f32_e32 v176, v127, v127
	s_waitcnt lgkmcnt(0)
	v_mul_f32_e32 v177, v129, v129
	v_fmac_f32_e32 v176, v126, v126
	v_fmac_f32_e32 v177, v128, v128
	v_add_f32_e32 v176, v176, v177
	v_mul_f32_e32 v177, v123, v123
	v_mul_f32_e32 v182, v125, v125
	v_fmac_f32_e32 v177, v122, v122
	v_fmac_f32_e32 v182, v124, v124
	v_add_f32_e32 v177, v177, v182
	v_add_f32_e32 v176, v176, v177
	v_mul_f32_e32 v177, v119, v119
	v_mul_f32_e32 v182, v121, v121
	v_fmac_f32_e32 v177, v118, v118
	v_fmac_f32_e32 v182, v120, v120
	v_add_f32_e32 v177, v177, v182
	v_add_f32_e32 v176, v176, v177
	v_mul_f32_e32 v177, v115, v115
	v_mul_f32_e32 v182, v117, v117
	v_fmac_f32_e32 v177, v114, v114
	v_fmac_f32_e32 v182, v116, v116
	v_add_f32_e32 v177, v177, v182
	v_add_f32_e32 v176, v176, v177
	v_mov_b32_e32 v177, v176
	s_nop 1
	v_permlane16_swap_b32_e32 v177, v176
	s_waitcnt lgkmcnt(0)
	v_add_f32_e32 v176, v176, v177
	v_mov_b32_e32 v177, v176
	s_nop 1
	v_permlane32_swap_b32_e32 v177, v176
	s_and_saveexec_b64 s[14:15], s[42:43]
	s_cbranch_execz .LBB0_1144
	s_waitcnt lgkmcnt(0)
	v_add_f32_e32 v176, v176, v177
	ds_write_b32 v224, v176 offset:256
.LBB0_1144:
	s_or_b64 exec, exec, s[14:15]
	v_mul_f32_e32 v176, v111, v111
	s_waitcnt lgkmcnt(0)
	v_mul_f32_e32 v177, v113, v113
	v_fmac_f32_e32 v176, v110, v110
	v_fmac_f32_e32 v177, v112, v112
	v_add_f32_e32 v176, v176, v177
	v_mul_f32_e32 v177, v107, v107
	v_mul_f32_e32 v182, v109, v109
	v_fmac_f32_e32 v177, v106, v106
	v_fmac_f32_e32 v182, v108, v108
	v_add_f32_e32 v177, v177, v182
	v_add_f32_e32 v176, v176, v177
	v_mul_f32_e32 v177, v87, v87
	v_mul_f32_e32 v182, v89, v89
	v_fmac_f32_e32 v177, v86, v86
	v_fmac_f32_e32 v182, v88, v88
	v_add_f32_e32 v177, v177, v182
	v_add_f32_e32 v176, v176, v177
	v_mul_f32_e32 v177, v83, v83
	v_mul_f32_e32 v182, v85, v85
	v_fmac_f32_e32 v177, v82, v82
	v_fmac_f32_e32 v182, v84, v84
	v_add_f32_e32 v177, v177, v182
	v_add_f32_e32 v176, v176, v177
	v_mov_b32_e32 v177, v176
	s_nop 1
	v_permlane16_swap_b32_e32 v177, v176
	s_waitcnt lgkmcnt(0)
	v_add_f32_e32 v176, v176, v177
	v_mov_b32_e32 v177, v176
	s_nop 1
	v_permlane32_swap_b32_e32 v177, v176
	s_and_saveexec_b64 s[14:15], s[42:43]
	s_cbranch_execz .LBB0_1146
	s_waitcnt lgkmcnt(0)
	v_add_f32_e32 v176, v176, v177
	ds_write_b32 v224, v176 offset:512
;     __device__ __forceinline__ void operator()(const f32x4 (&acc)[2][2][4][2], const Unit& u, int wr, int wc, int fr, int fq) const {
;     ...
;         for (int ai = 0; ai < 2; ++ai)
; #pragma unroll
;             for (int m = 0; m < 4; ++m) { float q = 0.f;
; #pragma unroll
;                 for (int bj = 0; bj < 2; ++bj)
; #pragma unroll
;                     for (int n = 0; n < 2; ++n) { const f32x4 x = acc[ai][bj][m][n]; q += (x[0] * x[0] + x[1] * x[1]) + (x[2] * x[2] + x[3] * x[3]); }
;                 q += __shfl_xor(q, 16); q += __shfl_xor(q, 32);
;                 if (fq == 0) P[(rloc0 + ai * 128 + m * 16) * 4 + wc] = q; }
.LBB0_1146:
	s_or_b64 exec, exec, s[14:15]
	v_mul_f32_e32 v176, v79, v79
	s_waitcnt lgkmcnt(0)
	v_mul_f32_e32 v177, v81, v81
	v_fmac_f32_e32 v176, v78, v78
	v_fmac_f32_e32 v177, v80, v80
	v_add_f32_e32 v176, v176, v177
	v_mul_f32_e32 v177, v75, v75
	v_mul_f32_e32 v182, v77, v77
	v_fmac_f32_e32 v177, v74, v74
	v_fmac_f32_e32 v182, v76, v76
	v_add_f32_e32 v177, v177, v182
	v_add_f32_e32 v176, v176, v177
	v_mul_f32_e32 v177, v71, v71
	v_mul_f32_e32 v182, v73, v73
	v_fmac_f32_e32 v177, v70, v70
	v_fmac_f32_e32 v182, v72, v72
	v_add_f32_e32 v177, v177, v182
	v_add_f32_e32 v176, v176, v177
	v_mul_f32_e32 v177, v67, v67
	v_mul_f32_e32 v182, v69, v69
	v_fmac_f32_e32 v177, v66, v66
	v_fmac_f32_e32 v182, v68, v68
	v_add_f32_e32 v177, v177, v182
	v_add_f32_e32 v176, v176, v177
	v_mov_b32_e32 v177, v176
	s_nop 1
	v_permlane16_swap_b32_e32 v177, v176
	s_waitcnt lgkmcnt(0)
	v_add_f32_e32 v176, v176, v177
	v_mov_b32_e32 v177, v176
	s_nop 1
	v_permlane32_swap_b32_e32 v177, v176
	s_and_saveexec_b64 s[14:15], s[42:43]
	s_cbranch_execz .LBB0_1148
	s_waitcnt lgkmcnt(0)
	v_add_f32_e32 v176, v176, v177
	ds_write_b32 v224, v176 offset:768
.LBB0_1148:
	s_or_b64 exec, exec, s[14:15]
	v_mul_f32_e32 v176, v63, v63
	s_waitcnt lgkmcnt(0)
	v_mul_f32_e32 v177, v65, v65
	v_fmac_f32_e32 v176, v62, v62
	v_fmac_f32_e32 v177, v64, v64
	v_add_f32_e32 v176, v176, v177
	v_mul_f32_e32 v177, v59, v59
	v_mul_f32_e32 v182, v61, v61
	v_fmac_f32_e32 v177, v58, v58
	v_fmac_f32_e32 v182, v60, v60
	v_add_f32_e32 v177, v177, v182
	v_add_f32_e32 v176, v176, v177
	v_mul_f32_e32 v177, v55, v55
	v_mul_f32_e32 v182, v57, v57
	v_fmac_f32_e32 v177, v54, v54
	v_fmac_f32_e32 v182, v56, v56
	v_add_f32_e32 v177, v177, v182
	v_add_f32_e32 v176, v176, v177
	v_mul_f32_e32 v177, v51, v51
	v_mul_f32_e32 v182, v53, v53
	v_fmac_f32_e32 v177, v50, v50
	v_fmac_f32_e32 v182, v52, v52
	v_add_f32_e32 v177, v177, v182
	v_add_f32_e32 v176, v176, v177
	v_mov_b32_e32 v177, v176
	s_nop 1
	v_permlane16_swap_b32_e32 v177, v176
	s_waitcnt lgkmcnt(0)
	v_add_f32_e32 v176, v176, v177
	v_mov_b32_e32 v177, v176
	s_nop 1
	v_permlane32_swap_b32_e32 v177, v176
	s_and_saveexec_b64 s[14:15], s[42:43]
	s_cbranch_execz .LBB0_1150
	s_waitcnt lgkmcnt(0)
	v_add_f32_e32 v176, v176, v177
	ds_write_b32 v224, v176 offset:2048
.LBB0_1150:
	s_or_b64 exec, exec, s[14:15]
	v_mul_f32_e32 v176, v47, v47
	s_waitcnt lgkmcnt(0)
	v_mul_f32_e32 v177, v49, v49
	v_fmac_f32_e32 v176, v46, v46
	v_fmac_f32_e32 v177, v48, v48
	v_add_f32_e32 v176, v176, v177
	v_mul_f32_e32 v177, v43, v43
	v_mul_f32_e32 v182, v45, v45
	v_fmac_f32_e32 v177, v42, v42
	v_fmac_f32_e32 v182, v44, v44
	v_add_f32_e32 v177, v177, v182
	v_add_f32_e32 v176, v176, v177
	v_mul_f32_e32 v177, v39, v39
	v_mul_f32_e32 v182, v41, v41
	v_fmac_f32_e32 v177, v38, v38
	v_fmac_f32_e32 v182, v40, v40
	v_add_f32_e32 v177, v177, v182
	v_add_f32_e32 v176, v176, v177
	v_mul_f32_e32 v177, v35, v35
	v_mul_f32_e32 v182, v37, v37
	v_fmac_f32_e32 v177, v34, v34
	v_fmac_f32_e32 v182, v36, v36
	v_add_f32_e32 v177, v177, v182
	v_add_f32_e32 v176, v176, v177
	v_mov_b32_e32 v177, v176
	s_nop 1
	v_permlane16_swap_b32_e32 v177, v176
	s_waitcnt lgkmcnt(0)
	v_add_f32_e32 v176, v176, v177
	v_mov_b32_e32 v177, v176
	s_nop 1
	v_permlane32_swap_b32_e32 v177, v176
	s_and_saveexec_b64 s[14:15], s[42:43]
	s_cbranch_execz .LBB0_1152
	s_waitcnt lgkmcnt(0)
	v_add_f32_e32 v176, v176, v177
	ds_write_b32 v224, v176 offset:2304
.LBB0_1152:
	s_or_b64 exec, exec, s[14:15]
	v_mul_f32_e32 v176, v31, v31
	s_waitcnt lgkmcnt(0)
	v_mul_f32_e32 v177, v33, v33
	v_fmac_f32_e32 v176, v30, v30
	v_fmac_f32_e32 v177, v32, v32
	v_add_f32_e32 v176, v176, v177
	v_mul_f32_e32 v177, v27, v27
	v_mul_f32_e32 v182, v29, v29
	v_fmac_f32_e32 v177, v26, v26
	v_fmac_f32_e32 v182, v28, v28
	v_add_f32_e32 v177, v177, v182
	v_add_f32_e32 v176, v176, v177
	v_mul_f32_e32 v177, v23, v23
	v_mul_f32_e32 v182, v25, v25
	v_fmac_f32_e32 v177, v22, v22
	v_fmac_f32_e32 v182, v24, v24
	v_add_f32_e32 v177, v177, v182
	v_add_f32_e32 v176, v176, v177
	v_mul_f32_e32 v177, v19, v19
	v_mul_f32_e32 v182, v21, v21
	v_fmac_f32_e32 v177, v18, v18
	v_fmac_f32_e32 v182, v20, v20
	v_add_f32_e32 v177, v177, v182
	v_add_f32_e32 v176, v176, v177
	v_mov_b32_e32 v177, v176
	s_nop 1
	v_permlane16_swap_b32_e32 v177, v176
	s_waitcnt lgkmcnt(0)
	v_add_f32_e32 v176, v176, v177
	v_mov_b32_e32 v177, v176
	s_nop 1
	v_permlane32_swap_b32_e32 v177, v176
	s_and_saveexec_b64 s[14:15], s[42:43]
	s_cbranch_execz .LBB0_1154
	s_waitcnt lgkmcnt(0)
	v_add_f32_e32 v176, v176, v177
	ds_write_b32 v224, v176 offset:2560
.LBB0_1154:
	s_or_b64 exec, exec, s[14:15]
	v_mul_f32_e32 v176, v15, v15
	s_waitcnt lgkmcnt(0)
	v_mul_f32_e32 v177, v17, v17
	v_fmac_f32_e32 v176, v14, v14
	v_fmac_f32_e32 v177, v16, v16
	v_add_f32_e32 v176, v176, v177
	v_mul_f32_e32 v177, v11, v11
	v_mul_f32_e32 v182, v13, v13
	v_fmac_f32_e32 v177, v10, v10
	v_fmac_f32_e32 v182, v12, v12
	v_add_f32_e32 v177, v177, v182
	v_add_f32_e32 v176, v176, v177
	v_mul_f32_e32 v177, v7, v7
	v_mul_f32_e32 v182, v9, v9
	v_fmac_f32_e32 v177, v6, v6
	v_fmac_f32_e32 v182, v8, v8
	v_add_f32_e32 v177, v177, v182
	v_add_f32_e32 v176, v176, v177
	v_mul_f32_e32 v177, v3, v3
	v_mul_f32_e32 v182, v5, v5
	v_fmac_f32_e32 v177, v2, v2
	v_fmac_f32_e32 v182, v4, v4
	v_add_f32_e32 v177, v177, v182
	v_add_f32_e32 v176, v176, v177
	v_mov_b32_e32 v177, v176
	s_nop 1
	v_permlane16_swap_b32_e32 v177, v176
	s_waitcnt lgkmcnt(0)
	v_add_f32_e32 v176, v176, v177
	v_mov_b32_e32 v177, v176
	s_nop 1
	v_permlane32_swap_b32_e32 v177, v176
	s_and_saveexec_b64 s[14:15], s[42:43]
	s_cbranch_execz .LBB0_1156
	s_waitcnt lgkmcnt(0)
	v_add_f32_e32 v176, v176, v177
	ds_write_b32 v224, v176 offset:2816

; __device__ __forceinline__ unsigned cvt_pk_bf16(float lo, float hi) { unsigned r; asm volatile("v_cvt_pk_bf16_f32 %0, %1, %2" : "=v"(r) : "v"(lo), "v"(hi)); return r; }
; __device__ __forceinline__ void unpack8(const u32x4 w, float (&v)[8]) { v[0] = bf_lo(w.x); v[1] = bf_hi(w.x); v[2] = bf_lo(w.y); v[3] = bf_hi(w.y); v[4] = bf_lo(w.z); v[5] = bf_hi(w.z); v[6] = bf_lo(w.w); v[7] = bf_hi(w.w); }
;     __device__ __forceinline__ void operator()(const f32x4 (&acc)[2][2][4][2], const Unit& u, int wr, int wc, int fr, int fq) const {
;     ...
;         for (int ai = 0; ai < 2; ++ai)
; #pragma unroll
;             for (int m = 0; m < 4; ++m) { const int rloc = rloc0 + ai * 128 + m * 16; const float rs = S[rloc]; float q2 = 0.f;
;                 u32x4 cur[2]; cur[0] = pre[m][0]; cur[1] = pre[m][1];
;                 if (ai == 0) {
; #pragma unroll
;                     for (int bj = 0; bj < 2; ++bj) pre[m][bj] = *(const u32x4*)(HB + (grow0 + rloc + 128) * DM + colb + bj * 128); }
; #pragma unroll
;                 for (int bj = 0; bj < 2; ++bj) { float h[8]; unpack8(cur[bj], h);
; #pragma unroll
;                     for (int e = 0; e < 4; ++e) { h[e] += acc[ai][bj][m][0][e] * g[bj][0][e] * rs; h[4 + e] += acc[ai][bj][m][1][e] * g[bj][1][e] * rs; }
;                     if (OUT) { float* op = OUT + (grow0 + rloc) * DM + colb + bj * 128; *(f32x4*)op = (f32x4){h[0], h[1], h[2], h[3]}; *(f32x4*)(op + 4) = (f32x4){h[4], h[5], h[6], h[7]}; }
;                     else { u32x4 w; w.x = cvt_pk_bf16(h[0], h[1]); w.y = cvt_pk_bf16(h[2], h[3]); w.z = cvt_pk_bf16(h[4], h[5]); w.w = cvt_pk_bf16(h[6], h[7]);
;                         *(u32x4*)(HB + (grow0 + rloc) * DM + colb + bj * 128) = w; float qv[8]; unpack8(w, qv);
; #pragma unroll
;                         for (int e = 0; e < 8; ++e) q2 += qv[e] * qv[e]; } }
;                 q2 += __shfl_xor(q2, 16); q2 += __shfl_xor(q2, 32);
;                 if (fq == 0) P[rloc * 4 + wc] = q2; }
.LBB0_1171:
	s_or_b64 exec, exec, s[8:9]
	v_lshl_add_u64 v[174:175], s[58:59], 0, v[174:175]
	v_lshl_add_u64 v[204:205], v[218:219], 1, v[174:175]
	s_mov_b32 s8, 0x40000
	v_add_co_u32_e32 v176, vcc, s8, v204
	s_waitcnt vmcnt(0) lgkmcnt(0)
	s_barrier
	v_lshl_add_u64 v[174:175], v[204:205], 0, s[24:25]
	s_waitcnt lgkmcnt(0)
	v_addc_co_u32_e32 v177, vcc, 0, v205, vcc
	ds_read_b32 v221, v225
	global_load_dwordx4 v[182:185], v[176:177], off
	s_nop 0
	global_load_dwordx4 v[174:177], v[174:175], off offset:256
	s_waitcnt vmcnt(2)
	v_lshlrev_b32_e32 v241, 16, v180
	v_mul_f32_e32 v138, v138, v98
	v_lshlrev_b32_e32 v234, 16, v178
	v_and_b32_e32 v178, 0xffff0000, v178
	s_waitcnt lgkmcnt(0)
	v_fmac_f32_e32 v241, v138, v221
	v_mul_f32_e32 v138, v143, v103
	v_and_b32_e32 v180, 0xffff0000, v180
	v_fmac_f32_e32 v178, v138, v221
	v_mul_f32_e32 v138, v139, v99
	v_lshlrev_b32_e32 v235, 16, v179
	v_fmac_f32_e32 v180, v138, v221
	v_mul_f32_e32 v138, v144, v104
	v_lshlrev_b32_e32 v242, 16, v181
	v_fmac_f32_e32 v235, v138, v221
	v_mul_f32_e32 v138, v140, v100
	v_and_b32_e32 v179, 0xffff0000, v179
	v_fmac_f32_e32 v242, v138, v221
	v_mul_f32_e32 v138, v145, v105
	v_and_b32_e32 v181, 0xffff0000, v181
	v_mul_f32_e32 v142, v142, v102
	v_fmac_f32_e32 v179, v138, v221
	v_mul_f32_e32 v138, v141, v101
	v_fmac_f32_e32 v234, v142, v221
	v_fmac_f32_e32 v181, v138, v221
	v_cvt_pk_bf16_f32 v138, v234, v178
	v_cvt_pk_bf16_f32 v139, v235, v179
	v_cvt_pk_bf16_f32 v140, v241, v180
	v_cvt_pk_bf16_f32 v141, v242, v181
	global_store_dwordx4 v[204:205], v[138:141], off
	v_lshlrev_b32_e32 v142, 16, v138
	v_lshlrev_b32_e32 v143, 16, v139
	v_and_b32_e32 v138, 0xffff0000, v138
	v_mul_f32_e32 v138, v138, v138
	v_fmac_f32_e32 v138, v142, v142
	v_and_b32_e32 v139, 0xffff0000, v139
	v_fmac_f32_e32 v138, v143, v143
	v_lshlrev_b32_e32 v144, 16, v140
	v_fmac_f32_e32 v138, v139, v139
	v_and_b32_e32 v140, 0xffff0000, v140
	v_fmac_f32_e32 v138, v144, v144
	v_lshlrev_b32_e32 v143, 16, v172
	v_mul_f32_e32 v130, v130, v90
	v_lshlrev_b32_e32 v145, 16, v141
	v_fmac_f32_e32 v138, v140, v140
	v_and_b32_e32 v140, 0xffff0000, v170
	v_fmac_f32_e32 v143, v130, v221
	v_mul_f32_e32 v130, v135, v95
	v_and_b32_e32 v141, 0xffff0000, v141
	v_fmac_f32_e32 v138, v145, v145
	v_and_b32_e32 v144, 0xffff0000, v172
	v_fmac_f32_e32 v140, v130, v221
	v_mul_f32_e32 v130, v131, v91
	v_fmac_f32_e32 v138, v141, v141
	v_lshlrev_b32_e32 v141, 16, v171
	v_fmac_f32_e32 v144, v130, v221
	v_mul_f32_e32 v130, v136, v96
	v_lshlrev_b32_e32 v145, 16, v173
	v_fmac_f32_e32 v141, v130, v221
	v_mul_f32_e32 v130, v132, v92
	v_and_b32_e32 v142, 0xffff0000, v171
	v_fmac_f32_e32 v145, v130, v221
	v_mul_f32_e32 v130, v137, v97
	v_lshlrev_b32_e32 v139, 16, v170
	v_and_b32_e32 v170, 0xffff0000, v173
	v_mul_f32_e32 v134, v134, v94
	v_fmac_f32_e32 v142, v130, v221
	v_mul_f32_e32 v130, v133, v93
	v_fmac_f32_e32 v139, v134, v221
	v_fmac_f32_e32 v170, v130, v221
	v_cvt_pk_bf16_f32 v132, v139, v140
	v_cvt_pk_bf16_f32 v133, v141, v142
	v_cvt_pk_bf16_f32 v134, v143, v144
	v_cvt_pk_bf16_f32 v135, v145, v170
	global_store_dwordx4 v[204:205], v[132:135], off offset:256
	v_lshlrev_b32_e32 v130, 16, v132
	v_and_b32_e32 v131, 0xffff0000, v132
	v_fmac_f32_e32 v138, v130, v130
	v_lshlrev_b32_e32 v136, 16, v133
	v_fmac_f32_e32 v138, v131, v131
	v_and_b32_e32 v137, 0xffff0000, v133
	v_fmac_f32_e32 v138, v136, v136
	v_lshlrev_b32_e32 v139, 16, v134
	v_fmac_f32_e32 v138, v137, v137
	v_and_b32_e32 v140, 0xffff0000, v134
	v_fmac_f32_e32 v138, v139, v139
	v_lshlrev_b32_e32 v141, 16, v135
	v_fmac_f32_e32 v138, v140, v140
	v_and_b32_e32 v142, 0xffff0000, v135
	v_fmac_f32_e32 v138, v141, v141
	v_fmac_f32_e32 v138, v142, v142
	v_mov_b32_e32 v130, v138
	s_nop 1
	v_permlane16_swap_b32_e32 v130, v138
	s_waitcnt lgkmcnt(0)
	v_add_f32_e32 v130, v138, v130
	v_mov_b32_e32 v131, v130
	s_nop 1
	v_permlane32_swap_b32_e32 v131, v130
	s_and_saveexec_b64 s[8:9], s[42:43]
	s_cbranch_execz .LBB0_1173
	s_waitcnt lgkmcnt(0)
	v_add_f32_e32 v130, v130, v131
	ds_write_b32 v224, v130
.LBB0_1173:
	s_or_b64 exec, exec, s[8:9]
	v_lshl_add_u32 v130, v194, 2, s64
	ds_read_b32 v140, v130
	s_waitcnt lgkmcnt(1)
	v_lshl_add_u64 v[130:131], s[0:1], 0, v[194:195]
	v_lshlrev_b64 v[130:131], 11, v[130:131]
	v_lshl_add_u64 v[130:131], s[58:59], 0, v[130:131]
	v_lshl_add_u64 v[138:139], v[218:219], 1, v[130:131]
	v_add_co_u32_e32 v132, vcc, 0x40000, v138
	v_lshl_add_u64 v[130:131], v[138:139], 0, s[24:25]
	s_nop 0
	v_addc_co_u32_e32 v133, vcc, 0, v139, vcc
	global_load_dwordx4 v[134:137], v[132:133], off
	s_nop 0
	global_load_dwordx4 v[130:133], v[130:131], off offset:256
	v_lshlrev_b32_e32 v145, 16, v168
	v_mul_f32_e32 v122, v122, v98
	v_and_b32_e32 v142, 0xffff0000, v166
	s_waitcnt lgkmcnt(0)
; __device__ __forceinline__ unsigned cvt_pk_bf16(float lo, float hi) { unsigned r; asm volatile("v_cvt_pk_bf16_f32 %0, %1, %2" : "=v"(r) : "v"(lo), "v"(hi)); return r; }
; __device__ __forceinline__ void unpack8(const u32x4 w, float (&v)[8]) { v[0] = bf_lo(w.x); v[1] = bf_hi(w.x); v[2] = bf_lo(w.y); v[3] = bf_hi(w.y); v[4] = bf_lo(w.z); v[5] = bf_hi(w.z); v[6] = bf_lo(w.w); v[7] = bf_hi(w.w); }
;     __device__ __forceinline__ void operator()(const f32x4 (&acc)[2][2][4][2], const Unit& u, int wr, int wc, int fr, int fq) const {
;     ...
;         for (int ai = 0; ai < 2; ++ai)
; #pragma unroll
;             for (int m = 0; m < 4; ++m) { const int rloc = rloc0 + ai * 128 + m * 16; const float rs = S[rloc]; float q2 = 0.f;
;                 u32x4 cur[2]; cur[0] = pre[m][0]; cur[1] = pre[m][1];
;                 if (ai == 0) {
; #pragma unroll
;                     for (int bj = 0; bj < 2; ++bj) pre[m][bj] = *(const u32x4*)(HB + (grow0 + rloc + 128) * DM + colb + bj * 128); }
; #pragma unroll
;                 for (int bj = 0; bj < 2; ++bj) { float h[8]; unpack8(cur[bj], h);
; #pragma unroll
;                     for (int e = 0; e < 4; ++e) { h[e] += acc[ai][bj][m][0][e] * g[bj][0][e] * rs; h[4 + e] += acc[ai][bj][m][1][e] * g[bj][1][e] * rs; }
;                     if (OUT) { float* op = OUT + (grow0 + rloc) * DM + colb + bj * 128; *(f32x4*)op = (f32x4){h[0], h[1], h[2], h[3]}; *(f32x4*)(op + 4) = (f32x4){h[4], h[5], h[6], h[7]}; }
;                     else { u32x4 w; w.x = cvt_pk_bf16(h[0], h[1]); w.y = cvt_pk_bf16(h[2], h[3]); w.z = cvt_pk_bf16(h[4], h[5]); w.w = cvt_pk_bf16(h[6], h[7]);
;                         *(u32x4*)(HB + (grow0 + rloc) * DM + colb + bj * 128) = w; float qv[8]; unpack8(w, qv);
; #pragma unroll
;                         for (int e = 0; e < 8; ++e) q2 += qv[e] * qv[e]; } }
;                 q2 += __shfl_xor(q2, 16); q2 += __shfl_xor(q2, 32);
;                 if (fq == 0) P[rloc * 4 + wc] = q2; }
	v_fmac_f32_e32 v145, v122, v140
	v_mul_f32_e32 v122, v127, v103
	v_lshlrev_b32_e32 v141, 16, v166
	v_and_b32_e32 v166, 0xffff0000, v168
	v_fmac_f32_e32 v142, v122, v140
	v_mul_f32_e32 v122, v123, v99
	v_lshlrev_b32_e32 v143, 16, v167
	v_fmac_f32_e32 v166, v122, v140
	v_mul_f32_e32 v122, v128, v104
	v_and_b32_e32 v144, 0xffff0000, v167
	v_lshlrev_b32_e32 v167, 16, v169
	v_fmac_f32_e32 v143, v122, v140
	v_mul_f32_e32 v122, v124, v100
	v_fmac_f32_e32 v167, v122, v140
	v_mul_f32_e32 v122, v129, v105
	v_and_b32_e32 v168, 0xffff0000, v169
	v_mul_f32_e32 v126, v126, v102
	v_fmac_f32_e32 v144, v122, v140
	v_mul_f32_e32 v122, v125, v101
	v_fmac_f32_e32 v141, v126, v140
	v_fmac_f32_e32 v168, v122, v140
	v_cvt_pk_bf16_f32 v122, v141, v142
	v_cvt_pk_bf16_f32 v123, v143, v144
	v_cvt_pk_bf16_f32 v124, v145, v166
	v_cvt_pk_bf16_f32 v125, v167, v168
	global_store_dwordx4 v[138:139], v[122:125], off
	v_lshlrev_b32_e32 v126, 16, v122
	v_lshlrev_b32_e32 v127, 16, v123
	v_and_b32_e32 v122, 0xffff0000, v122
	v_mul_f32_e32 v122, v122, v122
	v_fmac_f32_e32 v122, v126, v126
	v_and_b32_e32 v123, 0xffff0000, v123
	v_fmac_f32_e32 v122, v127, v127
	v_lshlrev_b32_e32 v128, 16, v124
	v_fmac_f32_e32 v122, v123, v123
	v_and_b32_e32 v124, 0xffff0000, v124
	v_fmac_f32_e32 v122, v128, v128
	v_lshlrev_b32_e32 v127, 16, v164
	v_mul_f32_e32 v114, v114, v90
	v_lshlrev_b32_e32 v129, 16, v125
	v_fmac_f32_e32 v122, v124, v124
	v_and_b32_e32 v124, 0xffff0000, v162
	v_fmac_f32_e32 v127, v114, v140
	v_mul_f32_e32 v114, v119, v95
	v_and_b32_e32 v125, 0xffff0000, v125
	v_fmac_f32_e32 v122, v129, v129
	v_and_b32_e32 v128, 0xffff0000, v164
	v_fmac_f32_e32 v124, v114, v140
	v_mul_f32_e32 v114, v115, v91
	v_fmac_f32_e32 v122, v125, v125
	v_lshlrev_b32_e32 v125, 16, v163
	v_fmac_f32_e32 v128, v114, v140
	v_mul_f32_e32 v114, v120, v96
	v_lshlrev_b32_e32 v129, 16, v165
	v_fmac_f32_e32 v125, v114, v140
	v_mul_f32_e32 v114, v116, v92
	v_and_b32_e32 v126, 0xffff0000, v163
	v_fmac_f32_e32 v129, v114, v140
	v_mul_f32_e32 v114, v121, v97
	v_lshlrev_b32_e32 v123, 16, v162
	v_and_b32_e32 v141, 0xffff0000, v165
	v_mul_f32_e32 v118, v118, v94
	v_fmac_f32_e32 v126, v114, v140
	v_mul_f32_e32 v114, v117, v93
	v_fmac_f32_e32 v123, v118, v140
	v_fmac_f32_e32 v141, v114, v140
	v_cvt_pk_bf16_f32 v116, v123, v124
	v_cvt_pk_bf16_f32 v117, v125, v126
	v_cvt_pk_bf16_f32 v118, v127, v128
	v_cvt_pk_bf16_f32 v119, v129, v141
	global_store_dwordx4 v[138:139], v[116:119], off offset:256
	v_lshlrev_b32_e32 v114, 16, v116
	v_and_b32_e32 v115, 0xffff0000, v116
	v_fmac_f32_e32 v122, v114, v114
	v_lshlrev_b32_e32 v120, 16, v117
	v_fmac_f32_e32 v122, v115, v115
	v_and_b32_e32 v121, 0xffff0000, v117
	v_fmac_f32_e32 v122, v120, v120
	v_lshlrev_b32_e32 v123, 16, v118
	v_fmac_f32_e32 v122, v121, v121
	v_and_b32_e32 v124, 0xffff0000, v118
	v_fmac_f32_e32 v122, v123, v123
	v_lshlrev_b32_e32 v125, 16, v119
	v_fmac_f32_e32 v122, v124, v124
	v_and_b32_e32 v126, 0xffff0000, v119
	v_fmac_f32_e32 v122, v125, v125
	v_fmac_f32_e32 v122, v126, v126
	v_mov_b32_e32 v114, v122
	s_nop 1
	v_permlane16_swap_b32_e32 v114, v122
	s_waitcnt lgkmcnt(0)
	v_add_f32_e32 v114, v122, v114
	v_mov_b32_e32 v115, v114
	s_nop 1
	v_permlane32_swap_b32_e32 v115, v114
	s_and_saveexec_b64 s[8:9], s[42:43]
	s_cbranch_execz .LBB0_1175
	s_waitcnt lgkmcnt(0)
	v_add_f32_e32 v114, v114, v115
	ds_write_b32 v228, v114
.LBB0_1175:
	s_or_b64 exec, exec, s[8:9]
	v_lshl_add_u32 v114, v196, 2, s64
	ds_read_b32 v124, v114
	s_waitcnt lgkmcnt(1)
	v_lshl_add_u64 v[114:115], s[0:1], 0, v[196:197]
	v_lshlrev_b64 v[114:115], 11, v[114:115]
	v_lshl_add_u64 v[114:115], s[58:59], 0, v[114:115]
	v_lshl_add_u64 v[122:123], v[218:219], 1, v[114:115]
	v_add_co_u32_e32 v116, vcc, 0x40000, v122
	v_lshl_add_u64 v[114:115], v[122:123], 0, s[24:25]
	s_nop 0
	v_addc_co_u32_e32 v117, vcc, 0, v123, vcc
	global_load_dwordx4 v[118:121], v[116:117], off
	s_nop 0
	global_load_dwordx4 v[114:117], v[114:115], off offset:256
	v_lshlrev_b32_e32 v129, 16, v160
	v_mul_f32_e32 v106, v106, v98
	v_and_b32_e32 v126, 0xffff0000, v158
	s_waitcnt lgkmcnt(0)
	v_fmac_f32_e32 v129, v106, v124
	v_mul_f32_e32 v106, v111, v103
	v_and_b32_e32 v138, 0xffff0000, v160
	v_fmac_f32_e32 v126, v106, v124
	v_mul_f32_e32 v106, v107, v99
	v_lshlrev_b32_e32 v127, 16, v159
	v_fmac_f32_e32 v138, v106, v124
	v_mul_f32_e32 v106, v112, v104
	v_lshlrev_b32_e32 v139, 16, v161
	v_fmac_f32_e32 v127, v106, v124
	v_mul_f32_e32 v106, v108, v100
	v_and_b32_e32 v128, 0xffff0000, v159
	v_fmac_f32_e32 v139, v106, v124
	v_mul_f32_e32 v106, v113, v105
	v_lshlrev_b32_e32 v125, 16, v158
	v_and_b32_e32 v140, 0xffff0000, v161
	v_mul_f32_e32 v110, v110, v102
	v_fmac_f32_e32 v128, v106, v124
	v_mul_f32_e32 v106, v109, v101
	v_fmac_f32_e32 v125, v110, v124
	v_fmac_f32_e32 v140, v106, v124
	v_cvt_pk_bf16_f32 v106, v125, v126
	v_cvt_pk_bf16_f32 v107, v127, v128
	v_cvt_pk_bf16_f32 v108, v129, v138
	v_cvt_pk_bf16_f32 v109, v139, v140
	global_store_dwordx4 v[122:123], v[106:109], off
	v_lshlrev_b32_e32 v110, 16, v106
	v_lshlrev_b32_e32 v111, 16, v107
	v_and_b32_e32 v106, 0xffff0000, v106
	v_mul_f32_e32 v106, v106, v106
	v_fmac_f32_e32 v106, v110, v110
	v_and_b32_e32 v107, 0xffff0000, v107
	v_fmac_f32_e32 v106, v111, v111
	v_lshlrev_b32_e32 v112, 16, v108
	v_fmac_f32_e32 v106, v107, v107
	v_and_b32_e32 v108, 0xffff0000, v108
	v_fmac_f32_e32 v106, v112, v112
	v_lshlrev_b32_e32 v111, 16, v156
	v_mul_f32_e32 v82, v82, v90
	v_lshlrev_b32_e32 v113, 16, v109
	v_fmac_f32_e32 v106, v108, v108
	v_and_b32_e32 v108, 0xffff0000, v154
	v_fmac_f32_e32 v111, v82, v124
	v_mul_f32_e32 v82, v87, v95
	v_and_b32_e32 v109, 0xffff0000, v109
	v_fmac_f32_e32 v106, v113, v113
; __device__ __forceinline__ unsigned cvt_pk_bf16(float lo, float hi) { unsigned r; asm volatile("v_cvt_pk_bf16_f32 %0, %1, %2" : "=v"(r) : "v"(lo), "v"(hi)); return r; }
; __device__ __forceinline__ void unpack8(const u32x4 w, float (&v)[8]) { v[0] = bf_lo(w.x); v[1] = bf_hi(w.x); v[2] = bf_lo(w.y); v[3] = bf_hi(w.y); v[4] = bf_lo(w.z); v[5] = bf_hi(w.z); v[6] = bf_lo(w.w); v[7] = bf_hi(w.w); }
;     __device__ __forceinline__ void operator()(const f32x4 (&acc)[2][2][4][2], const Unit& u, int wr, int wc, int fr, int fq) const {
;     ...
;         for (int ai = 0; ai < 2; ++ai)
; #pragma unroll
;             for (int m = 0; m < 4; ++m) { const int rloc = rloc0 + ai * 128 + m * 16; const float rs = S[rloc]; float q2 = 0.f;
;                 u32x4 cur[2]; cur[0] = pre[m][0]; cur[1] = pre[m][1];
;                 if (ai == 0) {
; #pragma unroll
;                     for (int bj = 0; bj < 2; ++bj) pre[m][bj] = *(const u32x4*)(HB + (grow0 + rloc + 128) * DM + colb + bj * 128); }
; #pragma unroll
;                 for (int bj = 0; bj < 2; ++bj) { float h[8]; unpack8(cur[bj], h);
; #pragma unroll
;                     for (int e = 0; e < 4; ++e) { h[e] += acc[ai][bj][m][0][e] * g[bj][0][e] * rs; h[4 + e] += acc[ai][bj][m][1][e] * g[bj][1][e] * rs; }
;                     if (OUT) { float* op = OUT + (grow0 + rloc) * DM + colb + bj * 128; *(f32x4*)op = (f32x4){h[0], h[1], h[2], h[3]}; *(f32x4*)(op + 4) = (f32x4){h[4], h[5], h[6], h[7]}; }
;                     else { u32x4 w; w.x = cvt_pk_bf16(h[0], h[1]); w.y = cvt_pk_bf16(h[2], h[3]); w.z = cvt_pk_bf16(h[4], h[5]); w.w = cvt_pk_bf16(h[6], h[7]);
;                         *(u32x4*)(HB + (grow0 + rloc) * DM + colb + bj * 128) = w; float qv[8]; unpack8(w, qv);
; #pragma unroll
;                         for (int e = 0; e < 8; ++e) q2 += qv[e] * qv[e]; } }
;                 q2 += __shfl_xor(q2, 16); q2 += __shfl_xor(q2, 32);
;                 if (fq == 0) P[rloc * 4 + wc] = q2; }
	v_and_b32_e32 v112, 0xffff0000, v156
	v_fmac_f32_e32 v108, v82, v124
	v_mul_f32_e32 v82, v83, v91
	v_fmac_f32_e32 v106, v109, v109
	v_lshlrev_b32_e32 v109, 16, v155
	v_fmac_f32_e32 v112, v82, v124
	v_mul_f32_e32 v82, v88, v96
	v_lshlrev_b32_e32 v113, 16, v157
	v_fmac_f32_e32 v109, v82, v124
	v_mul_f32_e32 v82, v84, v92
	v_and_b32_e32 v110, 0xffff0000, v155
	v_fmac_f32_e32 v113, v82, v124
	v_mul_f32_e32 v82, v89, v97
	v_lshlrev_b32_e32 v107, 16, v154
	v_and_b32_e32 v125, 0xffff0000, v157
	v_mul_f32_e32 v86, v86, v94
	v_fmac_f32_e32 v110, v82, v124
	v_mul_f32_e32 v82, v85, v93
	v_fmac_f32_e32 v107, v86, v124
	v_fmac_f32_e32 v125, v82, v124
	v_cvt_pk_bf16_f32 v84, v107, v108
	v_cvt_pk_bf16_f32 v85, v109, v110
	v_cvt_pk_bf16_f32 v86, v111, v112
	v_cvt_pk_bf16_f32 v87, v113, v125
	global_store_dwordx4 v[122:123], v[84:87], off offset:256
	v_lshlrev_b32_e32 v82, 16, v84
	v_and_b32_e32 v83, 0xffff0000, v84
	v_fmac_f32_e32 v106, v82, v82
	v_lshlrev_b32_e32 v88, 16, v85
	v_fmac_f32_e32 v106, v83, v83
	v_and_b32_e32 v89, 0xffff0000, v85
	v_fmac_f32_e32 v106, v88, v88
	v_lshlrev_b32_e32 v107, 16, v86
	v_fmac_f32_e32 v106, v89, v89
	v_and_b32_e32 v108, 0xffff0000, v86
	v_fmac_f32_e32 v106, v107, v107
	v_lshlrev_b32_e32 v109, 16, v87
	v_fmac_f32_e32 v106, v108, v108
	v_and_b32_e32 v110, 0xffff0000, v87
	v_fmac_f32_e32 v106, v109, v109
	v_fmac_f32_e32 v106, v110, v110
	v_mov_b32_e32 v82, v106
	s_nop 1
	v_permlane16_swap_b32_e32 v82, v106
	s_waitcnt lgkmcnt(0)
	v_add_f32_e32 v82, v106, v82
	v_mov_b32_e32 v83, v82
	s_nop 1
	v_permlane32_swap_b32_e32 v83, v82
	s_and_saveexec_b64 s[8:9], s[42:43]
	s_cbranch_execz .LBB0_1177
	s_waitcnt lgkmcnt(0)
	v_add_f32_e32 v82, v82, v83
	ds_write_b32 v229, v82
.LBB0_1177:
	s_or_b64 exec, exec, s[8:9]
	v_lshl_add_u32 v82, v198, 2, s64
	ds_read_b32 v108, v82
	s_waitcnt lgkmcnt(1)
	v_lshl_add_u64 v[82:83], s[0:1], 0, v[198:199]
	v_lshlrev_b64 v[82:83], 11, v[82:83]
	v_lshl_add_u64 v[82:83], s[58:59], 0, v[82:83]
	v_lshl_add_u64 v[106:107], v[218:219], 1, v[82:83]
	v_add_co_u32_e32 v84, vcc, 0x40000, v106
	v_lshl_add_u64 v[82:83], v[106:107], 0, s[24:25]
	s_nop 0
	v_addc_co_u32_e32 v85, vcc, 0, v107, vcc
	global_load_dwordx4 v[86:89], v[84:85], off
	s_nop 0
	global_load_dwordx4 v[82:85], v[82:83], off offset:256
	v_lshlrev_b32_e32 v113, 16, v152
	v_mul_f32_e32 v74, v74, v98
	v_and_b32_e32 v110, 0xffff0000, v150
	s_waitcnt lgkmcnt(0)
	v_fmac_f32_e32 v113, v74, v108
	v_mul_f32_e32 v74, v79, v103
	v_and_b32_e32 v122, 0xffff0000, v152
	v_fmac_f32_e32 v110, v74, v108
	v_mul_f32_e32 v74, v75, v99
	v_lshlrev_b32_e32 v111, 16, v151
	v_fmac_f32_e32 v122, v74, v108
	v_mul_f32_e32 v74, v80, v104
	v_lshlrev_b32_e32 v123, 16, v153
	v_fmac_f32_e32 v111, v74, v108
	v_mul_f32_e32 v74, v76, v100
	v_and_b32_e32 v112, 0xffff0000, v151
	v_fmac_f32_e32 v123, v74, v108
	v_mul_f32_e32 v74, v81, v105
	v_lshlrev_b32_e32 v109, 16, v150
	v_and_b32_e32 v124, 0xffff0000, v153
	v_mul_f32_e32 v78, v78, v102
	v_fmac_f32_e32 v112, v74, v108
	v_mul_f32_e32 v74, v77, v101
	v_fmac_f32_e32 v109, v78, v108
	v_fmac_f32_e32 v124, v74, v108
	v_cvt_pk_bf16_f32 v74, v109, v110
	v_cvt_pk_bf16_f32 v75, v111, v112
	v_cvt_pk_bf16_f32 v76, v113, v122
	v_cvt_pk_bf16_f32 v77, v123, v124
	global_store_dwordx4 v[106:107], v[74:77], off
	v_lshlrev_b32_e32 v78, 16, v74
	v_lshlrev_b32_e32 v79, 16, v75
	v_and_b32_e32 v74, 0xffff0000, v74
	v_mul_f32_e32 v74, v74, v74
	v_fmac_f32_e32 v74, v78, v78
	v_and_b32_e32 v75, 0xffff0000, v75
	v_fmac_f32_e32 v74, v79, v79
	v_lshlrev_b32_e32 v80, 16, v76
	v_fmac_f32_e32 v74, v75, v75
	v_and_b32_e32 v76, 0xffff0000, v76
	v_fmac_f32_e32 v74, v80, v80
	v_lshlrev_b32_e32 v79, 16, v148
	v_mul_f32_e32 v66, v66, v90
	v_lshlrev_b32_e32 v81, 16, v77
	v_fmac_f32_e32 v74, v76, v76
	v_and_b32_e32 v76, 0xffff0000, v146
	v_fmac_f32_e32 v79, v66, v108
	v_mul_f32_e32 v66, v71, v95
	v_and_b32_e32 v77, 0xffff0000, v77
	v_fmac_f32_e32 v74, v81, v81
	v_and_b32_e32 v80, 0xffff0000, v148
	v_fmac_f32_e32 v76, v66, v108
	v_mul_f32_e32 v66, v67, v91
	v_fmac_f32_e32 v74, v77, v77
	v_lshlrev_b32_e32 v77, 16, v147
	v_fmac_f32_e32 v80, v66, v108
	v_mul_f32_e32 v66, v72, v96
	v_lshlrev_b32_e32 v81, 16, v149
	v_fmac_f32_e32 v77, v66, v108
	v_mul_f32_e32 v66, v68, v92
	v_and_b32_e32 v78, 0xffff0000, v147
	v_fmac_f32_e32 v81, v66, v108
	v_mul_f32_e32 v66, v73, v97
	v_lshlrev_b32_e32 v75, 16, v146
	v_and_b32_e32 v109, 0xffff0000, v149
	v_mul_f32_e32 v70, v70, v94
	v_fmac_f32_e32 v78, v66, v108
	v_mul_f32_e32 v66, v69, v93
	v_fmac_f32_e32 v75, v70, v108
	v_fmac_f32_e32 v109, v66, v108
	v_cvt_pk_bf16_f32 v68, v75, v76
	v_cvt_pk_bf16_f32 v69, v77, v78
	v_cvt_pk_bf16_f32 v70, v79, v80
	v_cvt_pk_bf16_f32 v71, v81, v109
	global_store_dwordx4 v[106:107], v[68:71], off offset:256
	v_lshlrev_b32_e32 v66, 16, v68
	v_and_b32_e32 v67, 0xffff0000, v68
	v_fmac_f32_e32 v74, v66, v66
	v_lshlrev_b32_e32 v72, 16, v69
	v_fmac_f32_e32 v74, v67, v67
	v_and_b32_e32 v73, 0xffff0000, v69
	v_fmac_f32_e32 v74, v72, v72
	v_lshlrev_b32_e32 v75, 16, v70
	v_fmac_f32_e32 v74, v73, v73
	v_and_b32_e32 v76, 0xffff0000, v70
	v_fmac_f32_e32 v74, v75, v75
	v_lshlrev_b32_e32 v77, 16, v71
	v_fmac_f32_e32 v74, v76, v76
	v_and_b32_e32 v78, 0xffff0000, v71
	v_fmac_f32_e32 v74, v77, v77
	v_fmac_f32_e32 v74, v78, v78
	v_mov_b32_e32 v66, v74
	s_nop 1
	v_permlane16_swap_b32_e32 v66, v74
	s_waitcnt lgkmcnt(0)
	v_add_f32_e32 v66, v74, v66
	v_mov_b32_e32 v67, v66
	s_nop 1
	v_permlane32_swap_b32_e32 v67, v66
	s_and_saveexec_b64 s[8:9], s[42:43]
	s_cbranch_execz .LBB0_1179
	s_waitcnt lgkmcnt(0)
	v_add_f32_e32 v66, v66, v67
	ds_write_b32 v230, v66
; __device__ __forceinline__ unsigned cvt_pk_bf16(float lo, float hi) { unsigned r; asm volatile("v_cvt_pk_bf16_f32 %0, %1, %2" : "=v"(r) : "v"(lo), "v"(hi)); return r; }
; __device__ __forceinline__ void unpack8(const u32x4 w, float (&v)[8]) { v[0] = bf_lo(w.x); v[1] = bf_hi(w.x); v[2] = bf_lo(w.y); v[3] = bf_hi(w.y); v[4] = bf_lo(w.z); v[5] = bf_hi(w.z); v[6] = bf_lo(w.w); v[7] = bf_hi(w.w); }
;     __device__ __forceinline__ void operator()(const f32x4 (&acc)[2][2][4][2], const Unit& u, int wr, int wc, int fr, int fq) const {
;     ...
;         for (int ai = 0; ai < 2; ++ai)
; #pragma unroll
;             for (int m = 0; m < 4; ++m) { const int rloc = rloc0 + ai * 128 + m * 16; const float rs = S[rloc]; float q2 = 0.f;
;                 u32x4 cur[2]; cur[0] = pre[m][0]; cur[1] = pre[m][1];
;                 if (ai == 0) {
; #pragma unroll
;                     for (int bj = 0; bj < 2; ++bj) pre[m][bj] = *(const u32x4*)(HB + (grow0 + rloc + 128) * DM + colb + bj * 128); }
; #pragma unroll
;                 for (int bj = 0; bj < 2; ++bj) { float h[8]; unpack8(cur[bj], h);
; #pragma unroll
;                     for (int e = 0; e < 4; ++e) { h[e] += acc[ai][bj][m][0][e] * g[bj][0][e] * rs; h[4 + e] += acc[ai][bj][m][1][e] * g[bj][1][e] * rs; }
;                     if (OUT) { float* op = OUT + (grow0 + rloc) * DM + colb + bj * 128; *(f32x4*)op = (f32x4){h[0], h[1], h[2], h[3]}; *(f32x4*)(op + 4) = (f32x4){h[4], h[5], h[6], h[7]}; }
;                     else { u32x4 w; w.x = cvt_pk_bf16(h[0], h[1]); w.y = cvt_pk_bf16(h[2], h[3]); w.z = cvt_pk_bf16(h[4], h[5]); w.w = cvt_pk_bf16(h[6], h[7]);
;                         *(u32x4*)(HB + (grow0 + rloc) * DM + colb + bj * 128) = w; float qv[8]; unpack8(w, qv);
; #pragma unroll
;                         for (int e = 0; e < 8; ++e) q2 += qv[e] * qv[e]; } }
;                 q2 += __shfl_xor(q2, 16); q2 += __shfl_xor(q2, 32);
;                 if (fq == 0) P[rloc * 4 + wc] = q2; }
.LBB0_1179:
	s_or_b64 exec, exec, s[8:9]
	v_lshl_add_u32 v66, v200, 2, s64
	ds_read_b32 v68, v66
	s_waitcnt vmcnt(8)
	v_lshlrev_b32_e32 v73, 16, v184
	v_mul_f32_e32 v58, v58, v98
	v_and_b32_e32 v70, 0xffff0000, v182
	v_and_b32_e32 v74, 0xffff0000, v184
	s_waitcnt lgkmcnt(0)
	v_fmac_f32_e32 v73, v58, v68
	v_mul_f32_e32 v58, v63, v103
	v_fmac_f32_e32 v70, v58, v68
	v_mul_f32_e32 v58, v59, v99
	v_lshlrev_b32_e32 v71, 16, v183
	v_fmac_f32_e32 v74, v58, v68
	v_mul_f32_e32 v58, v64, v104
	v_lshl_add_u64 v[66:67], s[0:1], 0, v[200:201]
	v_lshlrev_b32_e32 v75, 16, v185
	v_fmac_f32_e32 v71, v58, v68
	v_mul_f32_e32 v58, v60, v100
	v_lshlrev_b64 v[66:67], 11, v[66:67]
	v_lshlrev_b32_e32 v69, 16, v182
	v_and_b32_e32 v72, 0xffff0000, v183
	v_mul_f32_e32 v62, v62, v102
	v_fmac_f32_e32 v75, v58, v68
	v_mul_f32_e32 v58, v65, v105
	v_and_b32_e32 v76, 0xffff0000, v185
	v_fmac_f32_e32 v69, v62, v68
	v_fmac_f32_e32 v72, v58, v68
	v_mul_f32_e32 v58, v61, v101
	v_lshl_add_u64 v[62:63], s[58:59], 0, v[66:67]
	v_fmac_f32_e32 v76, v58, v68
	v_cvt_pk_bf16_f32 v58, v69, v70
	v_lshl_add_u64 v[62:63], v[218:219], 1, v[62:63]
	v_cvt_pk_bf16_f32 v59, v71, v72
	v_cvt_pk_bf16_f32 v60, v73, v74
	v_cvt_pk_bf16_f32 v61, v75, v76
	global_store_dwordx4 v[62:63], v[58:61], off
	v_lshlrev_b32_e32 v64, 16, v58
	v_lshlrev_b32_e32 v65, 16, v59
	v_and_b32_e32 v58, 0xffff0000, v58
	v_mul_f32_e32 v58, v58, v58
	v_fmac_f32_e32 v58, v64, v64
	v_and_b32_e32 v59, 0xffff0000, v59
	v_fmac_f32_e32 v58, v65, v65
	v_lshlrev_b32_e32 v66, 16, v60
	v_fmac_f32_e32 v58, v59, v59
	v_and_b32_e32 v60, 0xffff0000, v60
	v_fmac_f32_e32 v58, v66, v66
	v_lshlrev_b32_e32 v65, 16, v176
	v_mul_f32_e32 v50, v50, v90
	v_lshlrev_b32_e32 v67, 16, v61
	v_fmac_f32_e32 v58, v60, v60
	v_and_b32_e32 v60, 0xffff0000, v174
	v_fmac_f32_e32 v65, v50, v68
	v_mul_f32_e32 v50, v55, v95
	v_and_b32_e32 v61, 0xffff0000, v61
	v_fmac_f32_e32 v58, v67, v67
	v_and_b32_e32 v66, 0xffff0000, v176
	v_fmac_f32_e32 v60, v50, v68
	v_mul_f32_e32 v50, v51, v91
	v_fmac_f32_e32 v58, v61, v61
	v_lshlrev_b32_e32 v61, 16, v175
	v_fmac_f32_e32 v66, v50, v68
	v_mul_f32_e32 v50, v56, v96
	v_lshlrev_b32_e32 v67, 16, v177
	v_fmac_f32_e32 v61, v50, v68
	v_mul_f32_e32 v50, v52, v92
	v_and_b32_e32 v64, 0xffff0000, v175
	v_fmac_f32_e32 v67, v50, v68
	v_mul_f32_e32 v50, v57, v97
	v_lshlrev_b32_e32 v59, 16, v174
	v_and_b32_e32 v69, 0xffff0000, v177
	v_mul_f32_e32 v54, v54, v94
	v_fmac_f32_e32 v64, v50, v68
	v_mul_f32_e32 v50, v53, v93
	v_fmac_f32_e32 v59, v54, v68
	v_fmac_f32_e32 v69, v50, v68
	v_cvt_pk_bf16_f32 v52, v59, v60
	v_cvt_pk_bf16_f32 v53, v61, v64
	v_cvt_pk_bf16_f32 v54, v65, v66
	v_cvt_pk_bf16_f32 v55, v67, v69
	global_store_dwordx4 v[62:63], v[52:55], off offset:256
	v_lshlrev_b32_e32 v50, 16, v52
	v_and_b32_e32 v51, 0xffff0000, v52
	v_fmac_f32_e32 v58, v50, v50
	v_lshlrev_b32_e32 v56, 16, v53
	v_fmac_f32_e32 v58, v51, v51
	v_and_b32_e32 v57, 0xffff0000, v53
	v_fmac_f32_e32 v58, v56, v56
	v_lshlrev_b32_e32 v59, 16, v54
	v_fmac_f32_e32 v58, v57, v57
	v_and_b32_e32 v60, 0xffff0000, v54
	v_fmac_f32_e32 v58, v59, v59
	v_lshlrev_b32_e32 v61, 16, v55
	v_fmac_f32_e32 v58, v60, v60
	v_and_b32_e32 v64, 0xffff0000, v55
	v_fmac_f32_e32 v58, v61, v61
	v_fmac_f32_e32 v58, v64, v64
	v_mov_b32_e32 v50, v58
	s_nop 1
	v_permlane16_swap_b32_e32 v50, v58
	s_waitcnt lgkmcnt(0)
	v_add_f32_e32 v50, v58, v50
	v_mov_b32_e32 v51, v50
	s_nop 1
	v_permlane32_swap_b32_e32 v51, v50
	s_and_saveexec_b64 s[8:9], s[42:43]
	s_cbranch_execz .LBB0_1181
	s_waitcnt lgkmcnt(0)
	v_add_f32_e32 v50, v50, v51
	ds_write_b32 v231, v50
.LBB0_1181:
	s_or_b64 exec, exec, s[8:9]
	v_lshl_add_u32 v50, v208, 2, s64
	ds_read_b32 v52, v50
	s_waitcnt vmcnt(13)
	v_lshlrev_b32_e32 v57, 16, v136
	v_mul_f32_e32 v42, v42, v98
	v_and_b32_e32 v54, 0xffff0000, v134
	v_and_b32_e32 v58, 0xffff0000, v136
	s_waitcnt lgkmcnt(0)
	v_fmac_f32_e32 v57, v42, v52
	v_mul_f32_e32 v42, v47, v103
	v_fmac_f32_e32 v54, v42, v52
	v_mul_f32_e32 v42, v43, v99
	v_lshlrev_b32_e32 v55, 16, v135
	v_fmac_f32_e32 v58, v42, v52
	v_mul_f32_e32 v42, v48, v104
	v_lshl_add_u64 v[50:51], s[0:1], 0, v[208:209]
	v_lshlrev_b32_e32 v59, 16, v137
	v_fmac_f32_e32 v55, v42, v52
	v_mul_f32_e32 v42, v44, v100
	v_lshlrev_b64 v[50:51], 11, v[50:51]
	v_lshlrev_b32_e32 v53, 16, v134
	v_and_b32_e32 v56, 0xffff0000, v135
	v_mul_f32_e32 v46, v46, v102
	v_fmac_f32_e32 v59, v42, v52
	v_mul_f32_e32 v42, v49, v105
	v_and_b32_e32 v60, 0xffff0000, v137
	v_fmac_f32_e32 v53, v46, v52
	v_fmac_f32_e32 v56, v42, v52
	v_mul_f32_e32 v42, v45, v101
	v_lshl_add_u64 v[46:47], s[58:59], 0, v[50:51]
	v_fmac_f32_e32 v60, v42, v52
	v_cvt_pk_bf16_f32 v42, v53, v54
	v_lshl_add_u64 v[46:47], v[218:219], 1, v[46:47]
	v_cvt_pk_bf16_f32 v43, v55, v56
	v_cvt_pk_bf16_f32 v44, v57, v58
	v_cvt_pk_bf16_f32 v45, v59, v60
	global_store_dwordx4 v[46:47], v[42:45], off
	v_lshlrev_b32_e32 v48, 16, v42
	v_lshlrev_b32_e32 v49, 16, v43
	v_and_b32_e32 v42, 0xffff0000, v42
	v_mul_f32_e32 v42, v42, v42
	v_fmac_f32_e32 v42, v48, v48
	v_and_b32_e32 v43, 0xffff0000, v43
	v_fmac_f32_e32 v42, v49, v49
	v_lshlrev_b32_e32 v50, 16, v44
	v_fmac_f32_e32 v42, v43, v43
	v_and_b32_e32 v44, 0xffff0000, v44
	v_fmac_f32_e32 v42, v50, v50
	s_waitcnt vmcnt(13)
; __device__ __forceinline__ unsigned cvt_pk_bf16(float lo, float hi) { unsigned r; asm volatile("v_cvt_pk_bf16_f32 %0, %1, %2" : "=v"(r) : "v"(lo), "v"(hi)); return r; }
; __device__ __forceinline__ void unpack8(const u32x4 w, float (&v)[8]) { v[0] = bf_lo(w.x); v[1] = bf_hi(w.x); v[2] = bf_lo(w.y); v[3] = bf_hi(w.y); v[4] = bf_lo(w.z); v[5] = bf_hi(w.z); v[6] = bf_lo(w.w); v[7] = bf_hi(w.w); }
;     __device__ __forceinline__ void operator()(const f32x4 (&acc)[2][2][4][2], const Unit& u, int wr, int wc, int fr, int fq) const {
;     ...
;         for (int ai = 0; ai < 2; ++ai)
; #pragma unroll
;             for (int m = 0; m < 4; ++m) { const int rloc = rloc0 + ai * 128 + m * 16; const float rs = S[rloc]; float q2 = 0.f;
;                 u32x4 cur[2]; cur[0] = pre[m][0]; cur[1] = pre[m][1];
;                 if (ai == 0) {
; #pragma unroll
;                     for (int bj = 0; bj < 2; ++bj) pre[m][bj] = *(const u32x4*)(HB + (grow0 + rloc + 128) * DM + colb + bj * 128); }
; #pragma unroll
;                 for (int bj = 0; bj < 2; ++bj) { float h[8]; unpack8(cur[bj], h);
; #pragma unroll
;                     for (int e = 0; e < 4; ++e) { h[e] += acc[ai][bj][m][0][e] * g[bj][0][e] * rs; h[4 + e] += acc[ai][bj][m][1][e] * g[bj][1][e] * rs; }
;                     if (OUT) { float* op = OUT + (grow0 + rloc) * DM + colb + bj * 128; *(f32x4*)op = (f32x4){h[0], h[1], h[2], h[3]}; *(f32x4*)(op + 4) = (f32x4){h[4], h[5], h[6], h[7]}; }
;                     else { u32x4 w; w.x = cvt_pk_bf16(h[0], h[1]); w.y = cvt_pk_bf16(h[2], h[3]); w.z = cvt_pk_bf16(h[4], h[5]); w.w = cvt_pk_bf16(h[6], h[7]);
;                         *(u32x4*)(HB + (grow0 + rloc) * DM + colb + bj * 128) = w; float qv[8]; unpack8(w, qv);
; #pragma unroll
;                         for (int e = 0; e < 8; ++e) q2 += qv[e] * qv[e]; } }
;                 q2 += __shfl_xor(q2, 16); q2 += __shfl_xor(q2, 32);
;                 if (fq == 0) P[rloc * 4 + wc] = q2; }
	v_lshlrev_b32_e32 v49, 16, v132
	v_mul_f32_e32 v34, v34, v90
	v_lshlrev_b32_e32 v51, 16, v45
	v_fmac_f32_e32 v42, v44, v44
	v_and_b32_e32 v44, 0xffff0000, v130
	v_fmac_f32_e32 v49, v34, v52
	v_mul_f32_e32 v34, v39, v95
	v_and_b32_e32 v45, 0xffff0000, v45
	v_fmac_f32_e32 v42, v51, v51
	v_and_b32_e32 v50, 0xffff0000, v132
	v_fmac_f32_e32 v44, v34, v52
	v_mul_f32_e32 v34, v35, v91
	v_fmac_f32_e32 v42, v45, v45
	v_lshlrev_b32_e32 v45, 16, v131
	v_fmac_f32_e32 v50, v34, v52
	v_mul_f32_e32 v34, v40, v96
	v_lshlrev_b32_e32 v51, 16, v133
	v_fmac_f32_e32 v45, v34, v52
	v_mul_f32_e32 v34, v36, v92
	v_and_b32_e32 v48, 0xffff0000, v131
	v_fmac_f32_e32 v51, v34, v52
	v_mul_f32_e32 v34, v41, v97
	v_lshlrev_b32_e32 v43, 16, v130
	v_and_b32_e32 v53, 0xffff0000, v133
	v_mul_f32_e32 v38, v38, v94
	v_fmac_f32_e32 v48, v34, v52
	v_mul_f32_e32 v34, v37, v93
	v_fmac_f32_e32 v43, v38, v52
	v_fmac_f32_e32 v53, v34, v52
	v_cvt_pk_bf16_f32 v36, v43, v44
	v_cvt_pk_bf16_f32 v37, v45, v48
	v_cvt_pk_bf16_f32 v38, v49, v50
	v_cvt_pk_bf16_f32 v39, v51, v53
	global_store_dwordx4 v[46:47], v[36:39], off offset:256
	v_lshlrev_b32_e32 v34, 16, v36
	v_and_b32_e32 v35, 0xffff0000, v36
	v_fmac_f32_e32 v42, v34, v34
	v_lshlrev_b32_e32 v40, 16, v37
	v_fmac_f32_e32 v42, v35, v35
	v_and_b32_e32 v41, 0xffff0000, v37
	v_fmac_f32_e32 v42, v40, v40
	v_lshlrev_b32_e32 v43, 16, v38
	v_fmac_f32_e32 v42, v41, v41
	v_and_b32_e32 v44, 0xffff0000, v38
	v_fmac_f32_e32 v42, v43, v43
	v_lshlrev_b32_e32 v45, 16, v39
	v_fmac_f32_e32 v42, v44, v44
	v_and_b32_e32 v48, 0xffff0000, v39
	v_fmac_f32_e32 v42, v45, v45
	v_fmac_f32_e32 v42, v48, v48
	v_mov_b32_e32 v34, v42
	s_nop 1
	v_permlane16_swap_b32_e32 v34, v42
	s_waitcnt lgkmcnt(0)
	v_add_f32_e32 v34, v42, v34
	v_mov_b32_e32 v35, v34
	s_nop 1
	v_permlane32_swap_b32_e32 v35, v34
	s_and_saveexec_b64 s[8:9], s[42:43]
	s_cbranch_execz .LBB0_1183
	s_waitcnt lgkmcnt(0)
	v_add_f32_e32 v34, v34, v35
	ds_write_b32 v232, v34
.LBB0_1183:
	s_or_b64 exec, exec, s[8:9]
	v_lshl_add_u32 v34, v210, 2, s64
	ds_read_b32 v36, v34
	s_waitcnt vmcnt(11)
	v_lshlrev_b32_e32 v41, 16, v120
	v_mul_f32_e32 v26, v26, v98
	v_and_b32_e32 v38, 0xffff0000, v118
	v_and_b32_e32 v42, 0xffff0000, v120
	s_waitcnt lgkmcnt(0)
	v_fmac_f32_e32 v41, v26, v36
	v_mul_f32_e32 v26, v31, v103
	v_fmac_f32_e32 v38, v26, v36
	v_mul_f32_e32 v26, v27, v99
	v_lshlrev_b32_e32 v39, 16, v119
	v_fmac_f32_e32 v42, v26, v36
	v_mul_f32_e32 v26, v32, v104
	v_lshl_add_u64 v[34:35], s[0:1], 0, v[210:211]
	v_lshlrev_b32_e32 v43, 16, v121
	v_fmac_f32_e32 v39, v26, v36
	v_mul_f32_e32 v26, v28, v100
	v_lshlrev_b64 v[34:35], 11, v[34:35]
	v_lshlrev_b32_e32 v37, 16, v118
	v_and_b32_e32 v40, 0xffff0000, v119
	v_mul_f32_e32 v30, v30, v102
	v_fmac_f32_e32 v43, v26, v36
	v_mul_f32_e32 v26, v33, v105
	v_and_b32_e32 v44, 0xffff0000, v121
	v_fmac_f32_e32 v37, v30, v36
	v_fmac_f32_e32 v40, v26, v36
	v_mul_f32_e32 v26, v29, v101
	v_lshl_add_u64 v[30:31], s[58:59], 0, v[34:35]
	v_fmac_f32_e32 v44, v26, v36
	v_cvt_pk_bf16_f32 v26, v37, v38
	v_lshl_add_u64 v[30:31], v[218:219], 1, v[30:31]
	v_cvt_pk_bf16_f32 v27, v39, v40
	v_cvt_pk_bf16_f32 v28, v41, v42
	v_cvt_pk_bf16_f32 v29, v43, v44
	global_store_dwordx4 v[30:31], v[26:29], off
	v_lshlrev_b32_e32 v32, 16, v26
	v_lshlrev_b32_e32 v33, 16, v27
	v_and_b32_e32 v26, 0xffff0000, v26
	v_mul_f32_e32 v26, v26, v26
	v_fmac_f32_e32 v26, v32, v32
	v_and_b32_e32 v27, 0xffff0000, v27
	v_fmac_f32_e32 v26, v33, v33
	v_lshlrev_b32_e32 v34, 16, v28
	v_fmac_f32_e32 v26, v27, v27
	v_and_b32_e32 v28, 0xffff0000, v28
	v_fmac_f32_e32 v26, v34, v34
	s_waitcnt vmcnt(11)
	v_lshlrev_b32_e32 v33, 16, v116
	v_mul_f32_e32 v18, v18, v90
	v_lshlrev_b32_e32 v35, 16, v29
	v_fmac_f32_e32 v26, v28, v28
	v_and_b32_e32 v28, 0xffff0000, v114
	v_fmac_f32_e32 v33, v18, v36
	v_mul_f32_e32 v18, v23, v95
	v_and_b32_e32 v29, 0xffff0000, v29
	v_fmac_f32_e32 v26, v35, v35
	v_and_b32_e32 v34, 0xffff0000, v116
	v_fmac_f32_e32 v28, v18, v36
	v_mul_f32_e32 v18, v19, v91
	v_fmac_f32_e32 v26, v29, v29
	v_lshlrev_b32_e32 v29, 16, v115
	v_fmac_f32_e32 v34, v18, v36
	v_mul_f32_e32 v18, v24, v96
	v_lshlrev_b32_e32 v35, 16, v117
	v_fmac_f32_e32 v29, v18, v36
	v_mul_f32_e32 v18, v20, v92
	v_and_b32_e32 v32, 0xffff0000, v115
	v_fmac_f32_e32 v35, v18, v36
	v_mul_f32_e32 v18, v25, v97
	v_lshlrev_b32_e32 v27, 16, v114
	v_and_b32_e32 v37, 0xffff0000, v117
	v_mul_f32_e32 v22, v22, v94
	v_fmac_f32_e32 v32, v18, v36
	v_mul_f32_e32 v18, v21, v93
	v_fmac_f32_e32 v27, v22, v36
	v_fmac_f32_e32 v37, v18, v36
	v_cvt_pk_bf16_f32 v20, v27, v28
	v_cvt_pk_bf16_f32 v21, v29, v32
	v_cvt_pk_bf16_f32 v22, v33, v34
	v_cvt_pk_bf16_f32 v23, v35, v37
	global_store_dwordx4 v[30:31], v[20:23], off offset:256
	v_lshlrev_b32_e32 v18, 16, v20
	v_and_b32_e32 v19, 0xffff0000, v20
	v_fmac_f32_e32 v26, v18, v18
	v_lshlrev_b32_e32 v24, 16, v21
	v_fmac_f32_e32 v26, v19, v19
	v_and_b32_e32 v25, 0xffff0000, v21
	v_fmac_f32_e32 v26, v24, v24
	v_lshlrev_b32_e32 v27, 16, v22
	v_fmac_f32_e32 v26, v25, v25
	v_and_b32_e32 v28, 0xffff0000, v22
	v_fmac_f32_e32 v26, v27, v27
	v_lshlrev_b32_e32 v29, 16, v23
	v_fmac_f32_e32 v26, v28, v28
	v_and_b32_e32 v32, 0xffff0000, v23
	v_fmac_f32_e32 v26, v29, v29
	v_fmac_f32_e32 v26, v32, v32
	v_mov_b32_e32 v18, v26
	s_nop 1
	v_permlane16_swap_b32_e32 v18, v26
	s_waitcnt lgkmcnt(0)
	v_add_f32_e32 v18, v26, v18
	v_mov_b32_e32 v19, v18
	s_nop 1
	v_permlane32_swap_b32_e32 v19, v18
	s_and_saveexec_b64 s[8:9], s[42:43]
	s_cbranch_execz .LBB0_1185
	s_waitcnt lgkmcnt(0)
	v_add_f32_e32 v18, v18, v19
	ds_write_b32 v233, v18
; __device__ __forceinline__ unsigned cvt_pk_bf16(float lo, float hi) { unsigned r; asm volatile("v_cvt_pk_bf16_f32 %0, %1, %2" : "=v"(r) : "v"(lo), "v"(hi)); return r; }
; __device__ __forceinline__ void unpack8(const u32x4 w, float (&v)[8]) { v[0] = bf_lo(w.x); v[1] = bf_hi(w.x); v[2] = bf_lo(w.y); v[3] = bf_hi(w.y); v[4] = bf_lo(w.z); v[5] = bf_hi(w.z); v[6] = bf_lo(w.w); v[7] = bf_hi(w.w); }
;     __device__ __forceinline__ void operator()(const f32x4 (&acc)[2][2][4][2], const Unit& u, int wr, int wc, int fr, int fq) const {
;     ...
;         for (int ai = 0; ai < 2; ++ai)
; #pragma unroll
;             for (int m = 0; m < 4; ++m) { const int rloc = rloc0 + ai * 128 + m * 16; const float rs = S[rloc]; float q2 = 0.f;
;                 u32x4 cur[2]; cur[0] = pre[m][0]; cur[1] = pre[m][1];
;                 if (ai == 0) {
; #pragma unroll
;                     for (int bj = 0; bj < 2; ++bj) pre[m][bj] = *(const u32x4*)(HB + (grow0 + rloc + 128) * DM + colb + bj * 128); }
; #pragma unroll
;                 for (int bj = 0; bj < 2; ++bj) { float h[8]; unpack8(cur[bj], h);
; #pragma unroll
;                     for (int e = 0; e < 4; ++e) { h[e] += acc[ai][bj][m][0][e] * g[bj][0][e] * rs; h[4 + e] += acc[ai][bj][m][1][e] * g[bj][1][e] * rs; }
;                     if (OUT) { float* op = OUT + (grow0 + rloc) * DM + colb + bj * 128; *(f32x4*)op = (f32x4){h[0], h[1], h[2], h[3]}; *(f32x4*)(op + 4) = (f32x4){h[4], h[5], h[6], h[7]}; }
;                     else { u32x4 w; w.x = cvt_pk_bf16(h[0], h[1]); w.y = cvt_pk_bf16(h[2], h[3]); w.z = cvt_pk_bf16(h[4], h[5]); w.w = cvt_pk_bf16(h[6], h[7]);
;                         *(u32x4*)(HB + (grow0 + rloc) * DM + colb + bj * 128) = w; float qv[8]; unpack8(w, qv);
; #pragma unroll
;                         for (int e = 0; e < 8; ++e) q2 += qv[e] * qv[e]; } }
;                 q2 += __shfl_xor(q2, 16); q2 += __shfl_xor(q2, 32);
;                 if (fq == 0) P[rloc * 4 + wc] = q2; }
.LBB0_1185:
	s_or_b64 exec, exec, s[8:9]
	ds_read_b32 v20, v226
	s_waitcnt vmcnt(9)
	v_lshlrev_b32_e32 v25, 16, v88
	v_mul_f32_e32 v10, v10, v98
	v_and_b32_e32 v22, 0xffff0000, v86
	v_and_b32_e32 v26, 0xffff0000, v88
	s_waitcnt lgkmcnt(0)
	v_fmac_f32_e32 v25, v10, v20
	v_mul_f32_e32 v10, v15, v103
	v_fmac_f32_e32 v22, v10, v20
	v_mul_f32_e32 v10, v11, v99
	v_lshlrev_b32_e32 v23, 16, v87
	v_fmac_f32_e32 v26, v10, v20
	v_mul_f32_e32 v10, v16, v104
	v_lshl_add_u64 v[18:19], s[0:1], 0, v[212:213]
	v_lshlrev_b32_e32 v27, 16, v89
	v_fmac_f32_e32 v23, v10, v20
	v_mul_f32_e32 v10, v12, v100
	v_lshlrev_b64 v[18:19], 11, v[18:19]
	v_lshlrev_b32_e32 v21, 16, v86
	v_and_b32_e32 v24, 0xffff0000, v87
	v_mul_f32_e32 v14, v14, v102
	v_fmac_f32_e32 v27, v10, v20
	v_mul_f32_e32 v10, v17, v105
	v_and_b32_e32 v28, 0xffff0000, v89
	v_fmac_f32_e32 v21, v14, v20
	v_fmac_f32_e32 v24, v10, v20
	v_mul_f32_e32 v10, v13, v101
	v_lshl_add_u64 v[14:15], s[58:59], 0, v[18:19]
	v_fmac_f32_e32 v28, v10, v20
	v_cvt_pk_bf16_f32 v10, v21, v22
	v_lshl_add_u64 v[14:15], v[218:219], 1, v[14:15]
	v_cvt_pk_bf16_f32 v11, v23, v24
	v_cvt_pk_bf16_f32 v12, v25, v26
	v_cvt_pk_bf16_f32 v13, v27, v28
	global_store_dwordx4 v[14:15], v[10:13], off
	v_lshlrev_b32_e32 v16, 16, v10
	v_lshlrev_b32_e32 v17, 16, v11
	v_and_b32_e32 v10, 0xffff0000, v10
	v_mul_f32_e32 v10, v10, v10
	v_fmac_f32_e32 v10, v16, v16
	v_and_b32_e32 v11, 0xffff0000, v11
	v_fmac_f32_e32 v10, v17, v17
	v_lshlrev_b32_e32 v18, 16, v12
	v_fmac_f32_e32 v10, v11, v11
	v_and_b32_e32 v12, 0xffff0000, v12
	v_fmac_f32_e32 v10, v18, v18
	s_waitcnt vmcnt(9)
	v_lshlrev_b32_e32 v17, 16, v84
	v_mul_f32_e32 v2, v2, v90
	v_lshlrev_b32_e32 v19, 16, v13
	v_fmac_f32_e32 v10, v12, v12
	v_and_b32_e32 v12, 0xffff0000, v82
	v_fmac_f32_e32 v17, v2, v20
	v_mul_f32_e32 v2, v7, v95
	v_and_b32_e32 v13, 0xffff0000, v13
	v_fmac_f32_e32 v10, v19, v19
	v_and_b32_e32 v18, 0xffff0000, v84
	v_fmac_f32_e32 v12, v2, v20
	v_mul_f32_e32 v2, v3, v91
	v_fmac_f32_e32 v10, v13, v13
	v_lshlrev_b32_e32 v13, 16, v83
	v_fmac_f32_e32 v18, v2, v20
	v_mul_f32_e32 v2, v8, v96
	v_lshlrev_b32_e32 v19, 16, v85
	v_fmac_f32_e32 v13, v2, v20
	v_mul_f32_e32 v2, v4, v92
	v_and_b32_e32 v16, 0xffff0000, v83
	v_fmac_f32_e32 v19, v2, v20
	v_mul_f32_e32 v2, v9, v97
	v_lshlrev_b32_e32 v11, 16, v82
	v_and_b32_e32 v21, 0xffff0000, v85
	v_mul_f32_e32 v6, v6, v94
	v_fmac_f32_e32 v16, v2, v20
	v_mul_f32_e32 v2, v5, v93
	v_fmac_f32_e32 v11, v6, v20
	v_fmac_f32_e32 v21, v2, v20
	v_cvt_pk_bf16_f32 v4, v11, v12
	v_cvt_pk_bf16_f32 v5, v13, v16
	v_cvt_pk_bf16_f32 v6, v17, v18
	v_cvt_pk_bf16_f32 v7, v19, v21
	global_store_dwordx4 v[14:15], v[4:7], off offset:256
	v_lshlrev_b32_e32 v2, 16, v4
	v_and_b32_e32 v3, 0xffff0000, v4
	v_fmac_f32_e32 v10, v2, v2
	v_lshlrev_b32_e32 v8, 16, v5
	v_fmac_f32_e32 v10, v3, v3
	v_and_b32_e32 v9, 0xffff0000, v5
	v_fmac_f32_e32 v10, v8, v8
	v_lshlrev_b32_e32 v11, 16, v6
	v_fmac_f32_e32 v10, v9, v9
	v_and_b32_e32 v12, 0xffff0000, v6
	v_fmac_f32_e32 v10, v11, v11
	v_lshlrev_b32_e32 v13, 16, v7
	v_fmac_f32_e32 v10, v12, v12
	v_and_b32_e32 v16, 0xffff0000, v7
	v_fmac_f32_e32 v10, v13, v13
	v_fmac_f32_e32 v10, v16, v16
	v_mov_b32_e32 v2, v10
	s_nop 1
	v_permlane16_swap_b32_e32 v2, v10
	s_waitcnt lgkmcnt(0)
	v_add_f32_e32 v2, v10, v2
	v_mov_b32_e32 v3, v2
	s_nop 1
	v_permlane32_swap_b32_e32 v3, v2
	s_and_saveexec_b64 s[8:9], s[42:43]
	s_cbranch_execz .LBB0_1187
	s_waitcnt lgkmcnt(0)
	v_add_f32_e32 v2, v2, v3
	ds_write_b32 v238, v2

;     __device__ __forceinline__ void operator()(const f32x4 (&acc)[2][2][4][2], const Unit& u, int wr, int wc, int fr, int fq) const {
;     ...
;         f32x4 g[2][2];
; #pragma unroll
;         for (int bj = 0; bj < 2; ++bj) { g[bj][0] = *(const f32x4*)(ga + colb + bj * 128); g[bj][1] = *(const f32x4*)(ga + colb + bj * 128 + 4); }
;         u32x4 pre[4][2];
; #pragma unroll
;         for (int m = 0; m < 4; ++m)
; #pragma unroll
;             for (int bj = 0; bj < 2; ++bj) pre[m][bj] = *(const u32x4*)(HB + (grow0 + rloc0 + m * 16) * DM + colb + bj * 128);
; #pragma unroll
;         for (int ai = 0; ai < 2; ++ai)
; #pragma unroll
;             for (int m = 0; m < 4; ++m) { float q = 0.f;
; #pragma unroll
;                 for (int bj = 0; bj < 2; ++bj)
; #pragma unroll
;                     for (int n = 0; n < 2; ++n) { const f32x4 x = acc[ai][bj][m][n]; q += (x[0] * x[0] + x[1] * x[1]) + (x[2] * x[2] + x[3] * x[3]); }
;                 q += __shfl_xor(q, 16); q += __shfl_xor(q, 32);
;                 if (fq == 0) P[(rloc0 + ai * 128 + m * 16) * 4 + wc] = q; }
.LBB0_1318:
	s_ashr_i32 s9, s8, 31
	v_lshl_or_b32 v218, s16, 8, v229
	s_lshl_b64 s[0:1], s[8:9], 8
	v_ashrrev_i32_e32 v219, 31, v218
	v_lshl_add_u64 v[222:223], s[0:1], 0, v[192:193]
	v_lshl_add_u64 v[130:131], v[218:219], 1, s[20:21]
	v_lshlrev_b64 v[162:163], 11, v[222:223]
	v_lshl_add_u64 v[130:131], v[130:131], 0, v[162:163]
	v_add_co_u32_e32 v132, vcc, s72, v130
	v_lshl_add_u64 v[62:63], v[218:219], 2, s[56:57]
	s_nop 0
	v_addc_co_u32_e32 v133, vcc, 0, v131, vcc
	s_mov_b32 s17, 0x10000
	global_load_dwordx4 v[74:77], v[62:63], off offset:16
	global_load_dwordx4 v[78:81], v[62:63], off
	global_load_dwordx4 v[58:61], v[62:63], off offset:528
	s_nop 0
	global_load_dwordx4 v[62:65], v[62:63], off offset:512
	s_nop 0
	global_load_dwordx4 v[182:185], v[130:131], off
	global_load_dwordx4 v[178:181], v[130:131], off offset:256
	global_load_dwordx4 v[174:177], v[132:133], off
	global_load_dwordx4 v[166:169], v[132:133], off offset:256
	v_add_co_u32_e32 v132, vcc, s17, v130
	s_mov_b32 s17, 0x18000
	s_nop 0
	v_addc_co_u32_e32 v133, vcc, 0, v131, vcc
	v_add_co_u32_e32 v130, vcc, s17, v130
	global_load_dwordx4 v[158:161], v[132:133], off
	global_load_dwordx4 v[154:157], v[132:133], off offset:256
	v_addc_co_u32_e32 v131, vcc, 0, v131, vcc
	global_load_dwordx4 v[142:145], v[130:131], off
	s_nop 0
	global_load_dwordx4 v[130:133], v[130:131], off offset:256
	v_and_b32_e32 v165, 64, v237
	v_xor_b32_e32 v164, 16, v237
	v_add_u32_e32 v165, 64, v165
	v_cmp_lt_i32_e32 vcc, v164, v165
	v_mul_f32_e32 v170, v153, v153
	v_fmac_f32_e32 v170, v152, v152
	v_cndmask_b32_e32 v164, v237, v164, vcc
	v_lshlrev_b32_e32 v245, 2, v164
	v_mul_f32_e32 v164, v151, v151
	v_fmac_f32_e32 v164, v150, v150
	v_add_f32_e32 v164, v164, v170
	v_mul_f32_e32 v170, v147, v147
	v_mul_f32_e32 v171, v149, v149
	v_fmac_f32_e32 v170, v146, v146
	v_fmac_f32_e32 v171, v148, v148
	v_add_f32_e32 v170, v170, v171
	v_add_f32_e32 v164, v164, v170
	v_mul_f32_e32 v170, v139, v139
	v_mul_f32_e32 v171, v141, v141
	v_fmac_f32_e32 v170, v138, v138
	v_fmac_f32_e32 v171, v140, v140
	v_add_f32_e32 v170, v170, v171
	v_add_f32_e32 v164, v164, v170
	v_mul_f32_e32 v170, v135, v135
	v_mul_f32_e32 v171, v137, v137
	v_fmac_f32_e32 v170, v134, v134
	v_fmac_f32_e32 v171, v136, v136
	v_add_f32_e32 v170, v170, v171
	v_add_f32_e32 v164, v164, v170
	v_mov_b32_e32 v170, v164
	s_nop 1
	v_permlane16_swap_b32_e32 v170, v164
	v_xor_b32_e32 v171, 32, v237
	v_cmp_lt_i32_e32 vcc, v171, v165
	s_waitcnt lgkmcnt(0)
	v_add_f32_e32 v164, v164, v170
	v_cndmask_b32_e32 v165, v237, v171, vcc
	v_lshlrev_b32_e32 v246, 2, v165
	v_mov_b32_e32 v165, v164
	s_nop 1
	v_permlane32_swap_b32_e32 v165, v164
	s_and_saveexec_b64 s[34:35], s[42:43]
	s_cbranch_execz .LBB0_1320
	s_waitcnt lgkmcnt(0)
	v_add_f32_e32 v164, v164, v165
	ds_write_b32 v230, v164
.LBB0_1320:
	s_or_b64 exec, exec, s[34:35]
	v_mul_f32_e32 v164, v127, v127
	s_waitcnt lgkmcnt(0)
	v_mul_f32_e32 v165, v129, v129
	v_fmac_f32_e32 v164, v126, v126
	v_fmac_f32_e32 v165, v128, v128
	v_add_f32_e32 v164, v164, v165
	v_mul_f32_e32 v165, v123, v123
	v_mul_f32_e32 v170, v125, v125
	v_fmac_f32_e32 v165, v122, v122
	v_fmac_f32_e32 v170, v124, v124
	v_add_f32_e32 v165, v165, v170
	v_add_f32_e32 v164, v164, v165
	v_mul_f32_e32 v165, v119, v119
	v_mul_f32_e32 v170, v121, v121
	v_fmac_f32_e32 v165, v118, v118
	v_fmac_f32_e32 v170, v120, v120
	v_add_f32_e32 v165, v165, v170
	v_add_f32_e32 v164, v164, v165
	v_mul_f32_e32 v165, v115, v115
	v_mul_f32_e32 v170, v117, v117
	v_fmac_f32_e32 v165, v114, v114
	v_fmac_f32_e32 v170, v116, v116
	v_add_f32_e32 v165, v165, v170
	v_add_f32_e32 v164, v164, v165
	v_mov_b32_e32 v165, v164
	s_nop 1
	v_permlane16_swap_b32_e32 v165, v164
	s_waitcnt lgkmcnt(0)
	v_add_f32_e32 v164, v164, v165
	v_mov_b32_e32 v165, v164
	s_nop 1
	v_permlane32_swap_b32_e32 v165, v164
	s_and_saveexec_b64 s[34:35], s[42:43]
	s_cbranch_execz .LBB0_1322
	s_waitcnt lgkmcnt(0)
	v_add_f32_e32 v164, v164, v165
	ds_write_b32 v230, v164 offset:256
.LBB0_1322:
	s_or_b64 exec, exec, s[34:35]
	v_mul_f32_e32 v164, v111, v111
	s_waitcnt lgkmcnt(0)
	v_mul_f32_e32 v165, v113, v113
	v_fmac_f32_e32 v164, v110, v110
	v_fmac_f32_e32 v165, v112, v112
	v_add_f32_e32 v164, v164, v165
	v_mul_f32_e32 v165, v107, v107
	v_mul_f32_e32 v170, v109, v109
	v_fmac_f32_e32 v165, v106, v106
	v_fmac_f32_e32 v170, v108, v108
	v_add_f32_e32 v165, v165, v170
	v_add_f32_e32 v164, v164, v165
	v_mul_f32_e32 v165, v103, v103
	v_mul_f32_e32 v170, v105, v105
	v_fmac_f32_e32 v165, v102, v102
	v_fmac_f32_e32 v170, v104, v104
	v_add_f32_e32 v165, v165, v170
	v_add_f32_e32 v164, v164, v165
	v_mul_f32_e32 v165, v99, v99
	v_mul_f32_e32 v170, v101, v101
	v_fmac_f32_e32 v165, v98, v98
	v_fmac_f32_e32 v170, v100, v100
	v_add_f32_e32 v165, v165, v170
	v_add_f32_e32 v164, v164, v165
	v_mov_b32_e32 v165, v164
	s_nop 1
	v_permlane16_swap_b32_e32 v165, v164
	s_waitcnt lgkmcnt(0)
	v_add_f32_e32 v164, v164, v165
	v_mov_b32_e32 v165, v164
	s_nop 1
	v_permlane32_swap_b32_e32 v165, v164
	s_and_saveexec_b64 s[34:35], s[42:43]
	s_cbranch_execz .LBB0_1324
	s_waitcnt lgkmcnt(0)
	v_add_f32_e32 v164, v164, v165
	ds_write_b32 v230, v164 offset:512
;     __device__ __forceinline__ void operator()(const f32x4 (&acc)[2][2][4][2], const Unit& u, int wr, int wc, int fr, int fq) const {
;     ...
;             for (int m = 0; m < 4; ++m) { float q = 0.f;
; #pragma unroll
;                 for (int bj = 0; bj < 2; ++bj)
; #pragma unroll
;                     for (int n = 0; n < 2; ++n) { const f32x4 x = acc[ai][bj][m][n]; q += (x[0] * x[0] + x[1] * x[1]) + (x[2] * x[2] + x[3] * x[3]); }
;                 q += __shfl_xor(q, 16); q += __shfl_xor(q, 32);
;                 if (fq == 0) P[(rloc0 + ai * 128 + m * 16) * 4 + wc] = q; }
.LBB0_1324:
	s_or_b64 exec, exec, s[34:35]
	v_mul_f32_e32 v164, v95, v95
	s_waitcnt lgkmcnt(0)
	v_mul_f32_e32 v165, v97, v97
	v_fmac_f32_e32 v164, v94, v94
	v_fmac_f32_e32 v165, v96, v96
	v_add_f32_e32 v164, v164, v165
	v_mul_f32_e32 v165, v91, v91
	v_mul_f32_e32 v170, v93, v93
	v_fmac_f32_e32 v165, v90, v90
	v_fmac_f32_e32 v170, v92, v92
	v_add_f32_e32 v165, v165, v170
	v_add_f32_e32 v164, v164, v165
	v_mul_f32_e32 v165, v87, v87
	v_mul_f32_e32 v170, v89, v89
	v_fmac_f32_e32 v165, v86, v86
	v_fmac_f32_e32 v170, v88, v88
	v_add_f32_e32 v165, v165, v170
	v_add_f32_e32 v164, v164, v165
	v_mul_f32_e32 v165, v83, v83
	v_mul_f32_e32 v170, v85, v85
	v_fmac_f32_e32 v165, v82, v82
	v_fmac_f32_e32 v170, v84, v84
	v_add_f32_e32 v165, v165, v170
	v_add_f32_e32 v164, v164, v165
	v_mov_b32_e32 v165, v164
	s_nop 1
	v_permlane16_swap_b32_e32 v165, v164
	s_waitcnt lgkmcnt(0)
	v_add_f32_e32 v164, v164, v165
	v_mov_b32_e32 v165, v164
	s_nop 1
	v_permlane32_swap_b32_e32 v165, v164
	s_and_saveexec_b64 s[34:35], s[42:43]
	s_cbranch_execz .LBB0_1326
	s_waitcnt lgkmcnt(0)
	v_add_f32_e32 v164, v164, v165
	ds_write_b32 v230, v164 offset:768
.LBB0_1326:
	s_or_b64 exec, exec, s[34:35]
	v_mul_f32_e32 v164, v71, v71
	s_waitcnt lgkmcnt(0)
	v_mul_f32_e32 v165, v73, v73
	v_fmac_f32_e32 v164, v70, v70
	v_fmac_f32_e32 v165, v72, v72
	v_add_f32_e32 v164, v164, v165
	v_mul_f32_e32 v165, v67, v67
	v_mul_f32_e32 v170, v69, v69
	v_fmac_f32_e32 v165, v66, v66
	v_fmac_f32_e32 v170, v68, v68
	v_add_f32_e32 v165, v165, v170
	v_add_f32_e32 v164, v164, v165
	v_mul_f32_e32 v165, v55, v55
	v_mul_f32_e32 v170, v57, v57
	v_fmac_f32_e32 v165, v54, v54
	v_fmac_f32_e32 v170, v56, v56
	v_add_f32_e32 v165, v165, v170
	v_add_f32_e32 v164, v164, v165
	v_mul_f32_e32 v165, v51, v51
	v_mul_f32_e32 v170, v53, v53
	v_fmac_f32_e32 v165, v50, v50
	v_fmac_f32_e32 v170, v52, v52
	v_add_f32_e32 v165, v165, v170
	v_add_f32_e32 v164, v164, v165
	v_mov_b32_e32 v165, v164
	s_nop 1
	v_permlane16_swap_b32_e32 v165, v164
	s_waitcnt lgkmcnt(0)
	v_add_f32_e32 v164, v164, v165
	v_mov_b32_e32 v165, v164
	s_nop 1
	v_permlane32_swap_b32_e32 v165, v164
	s_and_saveexec_b64 s[34:35], s[42:43]
	s_cbranch_execz .LBB0_1328
	s_waitcnt lgkmcnt(0)
	v_add_f32_e32 v164, v164, v165
	ds_write_b32 v230, v164 offset:2048
.LBB0_1328:
	s_or_b64 exec, exec, s[34:35]
	v_mul_f32_e32 v164, v47, v47
	s_waitcnt lgkmcnt(0)
	v_mul_f32_e32 v165, v49, v49
	v_fmac_f32_e32 v164, v46, v46
	v_fmac_f32_e32 v165, v48, v48
	v_add_f32_e32 v164, v164, v165
	v_mul_f32_e32 v165, v43, v43
	v_mul_f32_e32 v170, v45, v45
	v_fmac_f32_e32 v165, v42, v42
	v_fmac_f32_e32 v170, v44, v44
	v_add_f32_e32 v165, v165, v170
	v_add_f32_e32 v164, v164, v165
	v_mul_f32_e32 v165, v39, v39
	v_mul_f32_e32 v170, v41, v41
	v_fmac_f32_e32 v165, v38, v38
	v_fmac_f32_e32 v170, v40, v40
	v_add_f32_e32 v165, v165, v170
	v_add_f32_e32 v164, v164, v165
	v_mul_f32_e32 v165, v35, v35
	v_mul_f32_e32 v170, v37, v37
	v_fmac_f32_e32 v165, v34, v34
	v_fmac_f32_e32 v170, v36, v36
	v_add_f32_e32 v165, v165, v170
	v_add_f32_e32 v164, v164, v165
	v_mov_b32_e32 v165, v164
	s_nop 1
	v_permlane16_swap_b32_e32 v165, v164
	s_waitcnt lgkmcnt(0)
	v_add_f32_e32 v164, v164, v165
	v_mov_b32_e32 v165, v164
	s_nop 1
	v_permlane32_swap_b32_e32 v165, v164
	s_and_saveexec_b64 s[34:35], s[42:43]
	s_cbranch_execz .LBB0_1330
	s_waitcnt lgkmcnt(0)
	v_add_f32_e32 v164, v164, v165
	ds_write_b32 v230, v164 offset:2304
.LBB0_1330:
	s_or_b64 exec, exec, s[34:35]
	v_mul_f32_e32 v164, v31, v31
	s_waitcnt lgkmcnt(0)
	v_mul_f32_e32 v165, v33, v33
	v_fmac_f32_e32 v164, v30, v30
	v_fmac_f32_e32 v165, v32, v32
	v_add_f32_e32 v164, v164, v165
	v_mul_f32_e32 v165, v27, v27
	v_mul_f32_e32 v170, v29, v29
	v_fmac_f32_e32 v165, v26, v26
	v_fmac_f32_e32 v170, v28, v28
	v_add_f32_e32 v165, v165, v170
	v_add_f32_e32 v164, v164, v165
	v_mul_f32_e32 v165, v23, v23
	v_mul_f32_e32 v170, v25, v25
	v_fmac_f32_e32 v165, v22, v22
	v_fmac_f32_e32 v170, v24, v24
	v_add_f32_e32 v165, v165, v170
	v_add_f32_e32 v164, v164, v165
	v_mul_f32_e32 v165, v19, v19
	v_mul_f32_e32 v170, v21, v21
	v_fmac_f32_e32 v165, v18, v18
	v_fmac_f32_e32 v170, v20, v20
	v_add_f32_e32 v165, v165, v170
	v_add_f32_e32 v164, v164, v165
	v_mov_b32_e32 v165, v164
	s_nop 1
	v_permlane16_swap_b32_e32 v165, v164
	s_waitcnt lgkmcnt(0)
	v_add_f32_e32 v164, v164, v165
	v_mov_b32_e32 v165, v164
	s_nop 1
	v_permlane32_swap_b32_e32 v165, v164
	s_and_saveexec_b64 s[34:35], s[42:43]
	s_cbranch_execz .LBB0_1332
	s_waitcnt lgkmcnt(0)
	v_add_f32_e32 v164, v164, v165
	ds_write_b32 v230, v164 offset:2560
.LBB0_1332:
	s_or_b64 exec, exec, s[34:35]
	v_mul_f32_e32 v164, v15, v15
	s_waitcnt lgkmcnt(0)
	v_mul_f32_e32 v165, v17, v17
	v_fmac_f32_e32 v164, v14, v14
	v_fmac_f32_e32 v165, v16, v16
	v_add_f32_e32 v164, v164, v165
	v_mul_f32_e32 v165, v11, v11
	v_mul_f32_e32 v170, v13, v13
	v_fmac_f32_e32 v165, v10, v10
	v_fmac_f32_e32 v170, v12, v12
	v_add_f32_e32 v165, v165, v170
	v_add_f32_e32 v164, v164, v165
	v_mul_f32_e32 v165, v7, v7
	v_mul_f32_e32 v170, v9, v9
	v_fmac_f32_e32 v165, v6, v6
	v_fmac_f32_e32 v170, v8, v8
	v_add_f32_e32 v165, v165, v170
	v_add_f32_e32 v164, v164, v165
	v_mul_f32_e32 v165, v3, v3
	v_mul_f32_e32 v170, v5, v5
	v_fmac_f32_e32 v165, v2, v2
	v_fmac_f32_e32 v170, v4, v4
	v_add_f32_e32 v165, v165, v170
	v_add_f32_e32 v164, v164, v165
	v_mov_b32_e32 v165, v164
	s_nop 1
	v_permlane16_swap_b32_e32 v165, v164
	s_waitcnt lgkmcnt(0)
	v_add_f32_e32 v164, v164, v165
	v_mov_b32_e32 v165, v164
	s_nop 1
	v_permlane32_swap_b32_e32 v165, v164
	s_and_saveexec_b64 s[34:35], s[42:43]
	s_cbranch_execz .LBB0_1334
	s_waitcnt lgkmcnt(0)
	v_add_f32_e32 v164, v164, v165
	ds_write_b32 v230, v164 offset:2816

;     __device__ __forceinline__ void operator()(const f32x4 (&acc)[2][2][4][2], const Unit& u, int wr, int wc, int fr, int fq) const {
;     ...
;                 q2 += __shfl_xor(q2, 16); q2 += __shfl_xor(q2, 32);
;                 if (fq == 0) P[rloc * 4 + wc] = q2; }
.LBB0_1357:
	v_mov_b32_e32 v134, v184
	s_nop 1
	v_permlane16_swap_b32_e32 v134, v184
	s_waitcnt lgkmcnt(0)
	v_add_f32_e32 v134, v184, v134
	v_mov_b32_e32 v135, v134
	s_nop 1
	v_permlane32_swap_b32_e32 v135, v134
	s_and_saveexec_b64 s[8:9], s[42:43]
	s_cbranch_execz .LBB0_1359
	s_waitcnt lgkmcnt(0)
	v_add_f32_e32 v134, v134, v135
	ds_write_b32 v230, v134

;     __device__ __forceinline__ void operator()(const f32x4 (&acc)[2][2][4][2], const Unit& u, int wr, int wc, int fr, int fq) const {
;     ...
;                 q2 += __shfl_xor(q2, 16); q2 += __shfl_xor(q2, 32);
;                 if (fq == 0) P[rloc * 4 + wc] = q2; }
.LBB0_1367:
	v_mov_b32_e32 v114, v152
	s_nop 1
	v_permlane16_swap_b32_e32 v114, v152
	s_waitcnt lgkmcnt(0)
	v_add_f32_e32 v114, v152, v114
	v_mov_b32_e32 v115, v114
	s_nop 1
	v_permlane32_swap_b32_e32 v115, v114
	s_and_saveexec_b64 s[8:9], s[42:43]
	s_cbranch_execz .LBB0_1369
	s_waitcnt lgkmcnt(0)
	v_add_f32_e32 v114, v114, v115
	ds_write_b32 v238, v114

;     __device__ __forceinline__ void operator()(const f32x4 (&acc)[2][2][4][2], const Unit& u, int wr, int wc, int fr, int fq) const {
;     ...
;                 q2 += __shfl_xor(q2, 16); q2 += __shfl_xor(q2, 32);
;                 if (fq == 0) P[rloc * 4 + wc] = q2; }
.LBB0_1377:
	v_mov_b32_e32 v98, v128
	s_nop 1
	v_permlane16_swap_b32_e32 v98, v128
	s_waitcnt lgkmcnt(0)
	v_add_f32_e32 v98, v128, v98
	v_mov_b32_e32 v99, v98
	s_nop 1
	v_permlane32_swap_b32_e32 v99, v98
	s_and_saveexec_b64 s[8:9], s[42:43]
	s_cbranch_execz .LBB0_1379
	s_waitcnt lgkmcnt(0)
	v_add_f32_e32 v98, v98, v99
	ds_write_b32 v239, v98

;     __device__ __forceinline__ void operator()(const f32x4 (&acc)[2][2][4][2], const Unit& u, int wr, int wc, int fr, int fq) const {
;     ...
;                 q2 += __shfl_xor(q2, 16); q2 += __shfl_xor(q2, 32);
;                 if (fq == 0) P[rloc * 4 + wc] = q2; }
.LBB0_1387:
	v_mov_b32_e32 v82, v112
	s_nop 1
	v_permlane16_swap_b32_e32 v82, v112
	s_waitcnt lgkmcnt(0)
	v_add_f32_e32 v82, v112, v82
	v_mov_b32_e32 v83, v82
	s_nop 1
	v_permlane32_swap_b32_e32 v83, v82
	s_and_saveexec_b64 s[8:9], s[42:43]
	s_cbranch_execz .LBB0_1389
	s_waitcnt lgkmcnt(0)
	v_add_f32_e32 v82, v82, v83
	ds_write_b32 v240, v82

;     __device__ __forceinline__ void operator()(const f32x4 (&acc)[2][2][4][2], const Unit& u, int wr, int wc, int fr, int fq) const {
;     ...
;                 q2 += __shfl_xor(q2, 16); q2 += __shfl_xor(q2, 32);
;                 if (fq == 0) P[rloc * 4 + wc] = q2; }
.LBB0_1397:
	v_mov_b32_e32 v50, v88
	s_nop 1
	v_permlane16_swap_b32_e32 v50, v88
	s_waitcnt lgkmcnt(0)
	v_add_f32_e32 v50, v88, v50
	v_mov_b32_e32 v51, v50
	s_nop 1
	v_permlane32_swap_b32_e32 v51, v50
	s_and_saveexec_b64 s[8:9], s[42:43]
	s_cbranch_execz .LBB0_1399
	s_waitcnt lgkmcnt(0)
	v_add_f32_e32 v50, v50, v51
	ds_write_b32 v241, v50

;     __device__ __forceinline__ void operator()(const f32x4 (&acc)[2][2][4][2], const Unit& u, int wr, int wc, int fr, int fq) const {
;     ...
;                 q2 += __shfl_xor(q2, 16); q2 += __shfl_xor(q2, 32);
;                 if (fq == 0) P[rloc * 4 + wc] = q2; }
.LBB0_1407:
	v_mov_b32_e32 v34, v56
	s_nop 1
	v_permlane16_swap_b32_e32 v34, v56
	s_waitcnt lgkmcnt(0)
	v_add_f32_e32 v34, v56, v34
	v_mov_b32_e32 v35, v34
	s_nop 1
	v_permlane32_swap_b32_e32 v35, v34
	s_and_saveexec_b64 s[8:9], s[42:43]
	s_cbranch_execz .LBB0_1409
	s_waitcnt lgkmcnt(0)
	v_add_f32_e32 v34, v34, v35
	ds_write_b32 v242, v34

;     __device__ __forceinline__ void operator()(const f32x4 (&acc)[2][2][4][2], const Unit& u, int wr, int wc, int fr, int fq) const {
;     ...
;                 q2 += __shfl_xor(q2, 16); q2 += __shfl_xor(q2, 32);
;                 if (fq == 0) P[rloc * 4 + wc] = q2; }
.LBB0_1417:
	v_mov_b32_e32 v18, v40
	s_nop 1
	v_permlane16_swap_b32_e32 v18, v40
	s_waitcnt lgkmcnt(0)
	v_add_f32_e32 v18, v40, v18
	v_mov_b32_e32 v19, v18
	s_nop 1
	v_permlane32_swap_b32_e32 v19, v18
	s_and_saveexec_b64 s[8:9], s[42:43]
	s_cbranch_execz .LBB0_1419
	s_waitcnt lgkmcnt(0)
	v_add_f32_e32 v18, v18, v19
	ds_write_b32 v243, v18

;     __device__ __forceinline__ void operator()(const f32x4 (&acc)[2][2][4][2], const Unit& u, int wr, int wc, int fr, int fq) const {
;     ...
;                 q2 += __shfl_xor(q2, 16); q2 += __shfl_xor(q2, 32);
;                 if (fq == 0) P[rloc * 4 + wc] = q2; }
.LBB0_1427:
	v_mov_b32_e32 v2, v24
	s_nop 1
	v_permlane16_swap_b32_e32 v2, v24
	s_waitcnt lgkmcnt(0)
	v_add_f32_e32 v2, v24, v2
	v_mov_b32_e32 v3, v2
	s_nop 1
	v_permlane32_swap_b32_e32 v3, v2
	s_and_saveexec_b64 s[8:9], s[42:43]
	s_cbranch_execz .LBB0_1429
	s_waitcnt lgkmcnt(0)
	v_add_f32_e32 v2, v2, v3
	ds_write_b32 v244, v2
